# K-loops: load-cluster scalar base math hoisted into preceding MMA-cluster tail; loop-head a2/b2 select rotated to loop bottom (back-edge rotation)
# baseline (speedup 1.0000x reference)
; #define PG8_STAGE(bufoff, gbase, voff) do { _Pragma("unroll") for (int _i = 0; _i < 2; ++_i) \
;         __builtin_amdgcn_global_load_lds((const unsigned*)((const char*)(gbase) + (voff)[_i]), (LAS unsigned*)(lds + (bufoff) + ldsw + _i * 8192), 16, 0, 0); } while (0)
; #define PG8_LDA(dst, b, h) do { _Pragma("unroll") for (int m = 0; m < 4; ++m) _Pragma("unroll") for (int k = 0; k < 2; ++k) dst[m][k] = *(const LAS bf16x8*)(lds + PG8_SA(b, h) + aoff + m * 2048 + k * 1024); } while (0)
; #define PG8_LDB(dst, b, h) do { _Pragma("unroll") for (int n = 0; n < 2; ++n) _Pragma("unroll") for (int k = 0; k < 2; ++k) dst[n][k] = *(const LAS bf16x8*)(lds + PG8_SB(b, h) + boff + n * 2048 + k * 1024); } while (0)
; #define PG8_MMA(ai, bj, At, Bt) do { __builtin_amdgcn_s_setprio(1); _Pragma("unroll") for (int m = 0; m < 4; ++m) _Pragma("unroll") for (int n = 0; n < 2; ++n) _Pragma("unroll") for (int k = 0; k < 2; ++k) \
;         acc[ai][bj][m][n] = __builtin_amdgcn_mfma_f32_16x16x32_bf16(Bt[n][k], At[m][k], acc[ai][bj][m][n], 0, 0, 0); __builtin_amdgcn_s_setprio(0); } while (0)
; #define PG8_WAIT_V(n) asm volatile("s_waitcnt vmcnt(" #n ")" ::: "memory")
; #define PG8_WAIT_L(n) asm volatile("s_waitcnt lgkmcnt(" #n ")" ::: "memory")
; #define PG8_BAR __builtin_amdgcn_s_barrier()
; template <class Prog>
; __device__ __forceinline__ void gemm_phase(LAS unsigned char* lds, const int K, const Prog& S) {
;     ...
;         for (int t = 0; t < nt; t += 2) {
;             const bool last = (t == nt - 2);
;             const char* a1 = cA + (size_t)(t + 1) * kstep;
;             const char* a2 = last ? nA : cA + (size_t)(t + 2) * kstep; const char* b2 = last ? nB : cB + (size_t)(t + 2) * kstep;
;             const char* a3 = a2 + kstep; const char* b3 = b2 + kstep;
;             PG8_LDB(B0, 0, 0); PG8_SCHED; PG8_LDA(At, 0, 0); PG8_STAGE(PG8_SA(1, 1), a1 + hstep, voffA);
;             PG8_WAIT_L(8); PG8_BAR; PG8_WAIT_L(0); PG8_MMA(0, 0, At, B0); PG8_BAR; PG8_SCHED;
;             PG8_LDB(B1, 0, 1); PG8_STAGE(PG8_SB(0, 0), b2, voffB);
;             PG8_BAR; PG8_WAIT_L(0); PG8_MMA(0, 1, At, B1); PG8_BAR;
;             PG8_LDA(At, 0, 1); PG8_STAGE(PG8_SA(0, 0), a2, voffA);
;             PG8_BAR; PG8_WAIT_L(0); PG8_MMA(1, 0, At, B0); PG8_BAR; PG8_SCHED;
;             PG8_STAGE(PG8_SB(0, 1), b2 + hstep, voffB);
;             PG8_WAIT_V(6); PG8_BAR; PG8_MMA(1, 1, At, B1); PG8_BAR;
.LBB0_100:
	s_add_u32 s40, s40, 0x80080
	s_addc_u32 s41, s41, 0
	s_add_u32 s9, s44, 0x100
	s_addc_u32 s15, s45, 0
	s_mov_b32 s69, -2
	s_waitcnt vmcnt(16)
	v_add_u32_e32 v244, 0x10000, v205
	s_add_u32 s44, s40, 0xfff80080
	s_addc_u32 s45, s41, -1
	s_cmp_eq_u32 s69, 28
	s_cselect_b32 s47, s5, s45
	s_cselect_b32 s46, s4, s44
	s_cselect_b32 s45, s13, s15
	s_cselect_b32 s44, s12, s9
	s_add_u32 s76, s40, 0xfff80000
	s_addc_u32 s77, s41, -1
	ds_read_b128 v[128:131], v244
	ds_read_b128 v[132:135], v244 offset:1024
	ds_read_b128 v[136:139], v244 offset:2048
	ds_read_b128 v[140:143], v244 offset:3072
	s_add_i32 m0, s92, 0x8000
	ds_read_b128 v[188:191], v244 offset:16384
	ds_read_b128 v[196:199], v244 offset:17408
	ds_read_b128 v[200:203], v244 offset:18432
	ds_read_b128 v[218:221], v244 offset:19456
	global_load_lds_dwordx4 v184, s[76:77]
	s_add_i32 m0, s92, 0xa000
	ds_read_b128 v[144:147], v216
	ds_read_b128 v[148:151], v216 offset:1024
	ds_read_b128 v[152:155], v216 offset:2048
	ds_read_b128 v[156:159], v216 offset:3072
	global_load_lds_dwordx4 v186, s[76:77]
	s_add_i32 m0, s92, 0xc000
	ds_read_b128 v[160:163], v216 offset:4096
	ds_read_b128 v[164:167], v216 offset:5120
	ds_read_b128 v[168:171], v216 offset:6144
	ds_read_b128 v[172:175], v216 offset:7168
	global_load_lds_dwordx4 v184, s[40:41]
	s_add_i32 m0, s92, 0xe000
	s_nop 0
	global_load_lds_dwordx4 v186, s[40:41]
	s_waitcnt lgkmcnt(0)
	s_barrier
	v_mfma_f32_16x16x32_bf16 v[124:127], v[128:131], v[144:147], 0
	v_mfma_f32_16x16x32_bf16 v[116:119], v[136:139], v[144:147], 0
	v_mfma_f32_16x16x32_bf16 v[108:111], v[128:131], v[152:155], 0
	v_mfma_f32_16x16x32_bf16 v[100:103], v[136:139], v[152:155], 0
	v_mfma_f32_16x16x32_bf16 v[92:95], v[128:131], v[160:163], 0
	v_mfma_f32_16x16x32_bf16 v[84:87], v[136:139], v[160:163], 0
	v_mfma_f32_16x16x32_bf16 v[76:79], v[128:131], v[168:171], 0
	v_mfma_f32_16x16x32_bf16 v[68:71], v[136:139], v[168:171], 0
	v_mfma_f32_16x16x32_bf16 v[124:127], v[132:135], v[148:151], v[124:127]
	v_mfma_f32_16x16x32_bf16 v[116:119], v[140:143], v[148:151], v[116:119]
	v_mfma_f32_16x16x32_bf16 v[108:111], v[132:135], v[156:159], v[108:111]
	v_mfma_f32_16x16x32_bf16 v[100:103], v[140:143], v[156:159], v[100:103]
	v_mfma_f32_16x16x32_bf16 v[92:95], v[132:135], v[164:167], v[92:95]
	v_mfma_f32_16x16x32_bf16 v[84:87], v[140:143], v[164:167], v[84:87]
	v_mfma_f32_16x16x32_bf16 v[76:79], v[132:135], v[172:175], v[76:79]
	v_mfma_f32_16x16x32_bf16 v[68:71], v[140:143], v[172:175], v[68:71]
	v_mfma_f32_16x16x32_bf16 v[120:123], v[188:191], v[144:147], 0
	v_mfma_f32_16x16x32_bf16 v[112:115], v[200:203], v[144:147], 0
	v_mfma_f32_16x16x32_bf16 v[104:107], v[188:191], v[152:155], 0
	v_mfma_f32_16x16x32_bf16 v[96:99], v[200:203], v[152:155], 0
	v_mfma_f32_16x16x32_bf16 v[88:91], v[188:191], v[160:163], 0
	v_mfma_f32_16x16x32_bf16 v[80:83], v[200:203], v[160:163], 0
	v_mfma_f32_16x16x32_bf16 v[72:75], v[188:191], v[168:171], 0
	v_mfma_f32_16x16x32_bf16 v[64:67], v[200:203], v[168:171], 0
	v_mfma_f32_16x16x32_bf16 v[120:123], v[196:199], v[148:151], v[120:123]
	v_mfma_f32_16x16x32_bf16 v[112:115], v[218:221], v[148:151], v[112:115]
	v_mfma_f32_16x16x32_bf16 v[104:107], v[196:199], v[156:159], v[104:107]
	v_mfma_f32_16x16x32_bf16 v[96:99], v[218:221], v[156:159], v[96:99]
	v_mfma_f32_16x16x32_bf16 v[88:91], v[196:199], v[164:167], v[88:91]
	v_mfma_f32_16x16x32_bf16 v[80:83], v[218:221], v[164:167], v[80:83]
	v_mfma_f32_16x16x32_bf16 v[72:75], v[196:199], v[172:175], v[72:75]
	v_mfma_f32_16x16x32_bf16 v[64:67], v[218:221], v[172:175], v[64:67]
	s_add_u32 s76, s44, 0x80000
	s_addc_u32 s77, s45, 0
	s_barrier
	ds_read_b128 v[144:147], v216 offset:16384
	ds_read_b128 v[148:151], v216 offset:17408
	ds_read_b128 v[152:155], v216 offset:18432
	ds_read_b128 v[156:159], v216 offset:19456
	s_add_i32 m0, s92, 0x10000
	ds_read_b128 v[160:163], v216 offset:20480
	ds_read_b128 v[164:167], v216 offset:21504
	ds_read_b128 v[168:171], v216 offset:22528
	ds_read_b128 v[172:175], v216 offset:23552
	global_load_lds_dwordx4 v192, s[44:45]
	s_add_i32 m0, s92, 0x12000
	s_nop 0
	global_load_lds_dwordx4 v180, s[44:45]
	s_add_i32 m0, s92, 0x14000
	s_nop 0
	global_load_lds_dwordx4 v192, s[76:77]
	s_add_i32 m0, s92, 0x16000
	s_nop 0
	global_load_lds_dwordx4 v180, s[76:77]
	s_waitcnt vmcnt(4)
	s_waitcnt lgkmcnt(0)
	s_barrier
	v_mfma_f32_16x16x32_bf16 v[60:63], v[128:131], v[144:147], 0
	v_mfma_f32_16x16x32_bf16 v[52:55], v[136:139], v[144:147], 0
	v_mfma_f32_16x16x32_bf16 v[44:47], v[128:131], v[152:155], 0
	v_mfma_f32_16x16x32_bf16 v[36:39], v[136:139], v[152:155], 0
	v_mfma_f32_16x16x32_bf16 v[28:31], v[128:131], v[160:163], 0
	v_mfma_f32_16x16x32_bf16 v[20:23], v[136:139], v[160:163], 0
	v_mfma_f32_16x16x32_bf16 v[12:15], v[128:131], v[168:171], 0
	v_mfma_f32_16x16x32_bf16 v[4:7], v[136:139], v[168:171], 0
	v_mfma_f32_16x16x32_bf16 v[60:63], v[132:135], v[148:151], v[60:63]
	v_mfma_f32_16x16x32_bf16 v[52:55], v[140:143], v[148:151], v[52:55]
	v_mfma_f32_16x16x32_bf16 v[44:47], v[132:135], v[156:159], v[44:47]
	v_mfma_f32_16x16x32_bf16 v[36:39], v[140:143], v[156:159], v[36:39]
	v_mfma_f32_16x16x32_bf16 v[28:31], v[132:135], v[164:167], v[28:31]
	v_mfma_f32_16x16x32_bf16 v[20:23], v[140:143], v[164:167], v[20:23]
	v_mfma_f32_16x16x32_bf16 v[12:15], v[132:135], v[172:175], v[12:15]
	v_mfma_f32_16x16x32_bf16 v[4:7], v[140:143], v[172:175], v[4:7]
	v_mfma_f32_16x16x32_bf16 v[56:59], v[188:191], v[144:147], 0
	v_mfma_f32_16x16x32_bf16 v[48:51], v[200:203], v[144:147], 0
	v_mfma_f32_16x16x32_bf16 v[40:43], v[188:191], v[152:155], 0
	v_mfma_f32_16x16x32_bf16 v[32:35], v[200:203], v[152:155], 0
	v_mfma_f32_16x16x32_bf16 v[24:27], v[188:191], v[160:163], 0
	v_mfma_f32_16x16x32_bf16 v[16:19], v[200:203], v[160:163], 0
	v_mfma_f32_16x16x32_bf16 v[8:11], v[188:191], v[168:171], 0
	v_mfma_f32_16x16x32_bf16 v[0:3], v[200:203], v[168:171], 0
	v_mfma_f32_16x16x32_bf16 v[56:59], v[196:199], v[148:151], v[56:59]
	v_mfma_f32_16x16x32_bf16 v[48:51], v[218:221], v[148:151], v[48:51]
	v_mfma_f32_16x16x32_bf16 v[40:43], v[196:199], v[156:159], v[40:43]
	v_mfma_f32_16x16x32_bf16 v[32:35], v[218:221], v[156:159], v[32:35]
	v_mfma_f32_16x16x32_bf16 v[24:27], v[196:199], v[164:167], v[24:27]
	v_mfma_f32_16x16x32_bf16 v[16:19], v[218:221], v[164:167], v[16:19]
	v_mfma_f32_16x16x32_bf16 v[8:11], v[196:199], v[172:175], v[8:11]
	v_mfma_f32_16x16x32_bf16 v[0:3], v[218:221], v[172:175], v[0:3]
	s_add_u32 s76, s46, 0x80000
	s_addc_u32 s77, s47, 0
	s_barrier
; #define PG8_STAGE(bufoff, gbase, voff) do { _Pragma("unroll") for (int _i = 0; _i < 2; ++_i) \
;         __builtin_amdgcn_global_load_lds((const unsigned*)((const char*)(gbase) + (voff)[_i]), (LAS unsigned*)(lds + (bufoff) + ldsw + _i * 8192), 16, 0, 0); } while (0)
; #define PG8_LDA(dst, b, h) do { _Pragma("unroll") for (int m = 0; m < 4; ++m) _Pragma("unroll") for (int k = 0; k < 2; ++k) dst[m][k] = *(const LAS bf16x8*)(lds + PG8_SA(b, h) + aoff + m * 2048 + k * 1024); } while (0)
; #define PG8_LDB(dst, b, h) do { _Pragma("unroll") for (int n = 0; n < 2; ++n) _Pragma("unroll") for (int k = 0; k < 2; ++k) dst[n][k] = *(const LAS bf16x8*)(lds + PG8_SB(b, h) + boff + n * 2048 + k * 1024); } while (0)
; #define PG8_MMA(ai, bj, At, Bt) do { __builtin_amdgcn_s_setprio(1); _Pragma("unroll") for (int m = 0; m < 4; ++m) _Pragma("unroll") for (int n = 0; n < 2; ++n) _Pragma("unroll") for (int k = 0; k < 2; ++k) \
;         acc[ai][bj][m][n] = __builtin_amdgcn_mfma_f32_16x16x32_bf16(Bt[n][k], At[m][k], acc[ai][bj][m][n], 0, 0, 0); __builtin_amdgcn_s_setprio(0); } while (0)
; #define PG8_WAIT_V(n) asm volatile("s_waitcnt vmcnt(" #n ")" ::: "memory")
; #define PG8_WAIT_L(n) asm volatile("s_waitcnt lgkmcnt(" #n ")" ::: "memory")
; #define PG8_BAR __builtin_amdgcn_s_barrier()
; #define PG8_SCHED __builtin_amdgcn_sched_barrier(0)
; template <class Prog>
; __device__ __forceinline__ void gemm_phase(LAS unsigned char* lds, const int K, const Prog& S) {
;     ...
;             const char* a2 = last ? nA : cA + (size_t)(t + 2) * kstep; const char* b2 = last ? nB : cB + (size_t)(t + 2) * kstep;
;     ...
;             PG8_LDB(B0, 1, 0); PG8_SCHED; PG8_LDA(At, 1, 0); PG8_STAGE(PG8_SA(0, 1), a2 + hstep, voffA);
;             PG8_WAIT_L(8); PG8_BAR; PG8_WAIT_L(0); PG8_MMA(0, 0, At, B0); PG8_BAR; PG8_SCHED;
;             PG8_LDB(B1, 1, 1); PG8_STAGE(PG8_SB(1, 0), b3, voffB);
;             PG8_BAR; PG8_WAIT_L(0); PG8_MMA(0, 1, At, B1); PG8_BAR;
;             PG8_LDA(At, 1, 1); PG8_STAGE(PG8_SA(1, 0), a3, voffA);
;             PG8_BAR; PG8_WAIT_L(0); PG8_MMA(1, 0, At, B0); PG8_BAR; PG8_SCHED;
;             PG8_STAGE(PG8_SB(1, 1), b3 + hstep, voffB);
;             PG8_WAIT_V(6); PG8_BAR; PG8_MMA(1, 1, At, B1); PG8_BAR;
	ds_read_b128 v[128:131], v244 offset:32768
	ds_read_b128 v[132:135], v244 offset:33792
	ds_read_b128 v[136:139], v244 offset:34816
	ds_read_b128 v[140:143], v244 offset:35840
	s_mov_b32 m0, s92
	ds_read_b128 v[188:191], v244 offset:49152
	ds_read_b128 v[196:199], v244 offset:50176
	ds_read_b128 v[200:203], v244 offset:51200
	ds_read_b128 v[218:221], v244 offset:52224
	global_load_lds_dwordx4 v176, s[46:47]
	s_add_i32 m0, s92, 0x2000
	ds_read_b128 v[144:147], v216 offset:32768
	ds_read_b128 v[148:151], v216 offset:33792
	ds_read_b128 v[152:155], v216 offset:34816
	ds_read_b128 v[156:159], v216 offset:35840
	global_load_lds_dwordx4 v178, s[46:47]
	s_add_i32 m0, s92, 0x4000
	ds_read_b128 v[160:163], v216 offset:36864
	ds_read_b128 v[164:167], v216 offset:37888
	ds_read_b128 v[168:171], v216 offset:38912
	ds_read_b128 v[172:175], v216 offset:39936
	global_load_lds_dwordx4 v176, s[76:77]
	s_add_i32 m0, s92, 0x6000
	s_nop 0
	global_load_lds_dwordx4 v178, s[76:77]
	s_waitcnt lgkmcnt(0)
	s_barrier
	v_mfma_f32_16x16x32_bf16 v[124:127], v[128:131], v[144:147], v[124:127]
	v_mfma_f32_16x16x32_bf16 v[116:119], v[136:139], v[144:147], v[116:119]
	v_mfma_f32_16x16x32_bf16 v[108:111], v[128:131], v[152:155], v[108:111]
	v_mfma_f32_16x16x32_bf16 v[100:103], v[136:139], v[152:155], v[100:103]
	v_mfma_f32_16x16x32_bf16 v[92:95], v[128:131], v[160:163], v[92:95]
	v_mfma_f32_16x16x32_bf16 v[84:87], v[136:139], v[160:163], v[84:87]
	v_mfma_f32_16x16x32_bf16 v[76:79], v[128:131], v[168:171], v[76:79]
	v_mfma_f32_16x16x32_bf16 v[68:71], v[136:139], v[168:171], v[68:71]
	v_mfma_f32_16x16x32_bf16 v[124:127], v[132:135], v[148:151], v[124:127]
	v_mfma_f32_16x16x32_bf16 v[116:119], v[140:143], v[148:151], v[116:119]
	v_mfma_f32_16x16x32_bf16 v[108:111], v[132:135], v[156:159], v[108:111]
	v_mfma_f32_16x16x32_bf16 v[100:103], v[140:143], v[156:159], v[100:103]
	v_mfma_f32_16x16x32_bf16 v[92:95], v[132:135], v[164:167], v[92:95]
	v_mfma_f32_16x16x32_bf16 v[84:87], v[140:143], v[164:167], v[84:87]
	v_mfma_f32_16x16x32_bf16 v[76:79], v[132:135], v[172:175], v[76:79]
	v_mfma_f32_16x16x32_bf16 v[68:71], v[140:143], v[172:175], v[68:71]
	v_mfma_f32_16x16x32_bf16 v[120:123], v[188:191], v[144:147], v[120:123]
	v_mfma_f32_16x16x32_bf16 v[112:115], v[200:203], v[144:147], v[112:115]
	v_mfma_f32_16x16x32_bf16 v[104:107], v[188:191], v[152:155], v[104:107]
	v_mfma_f32_16x16x32_bf16 v[96:99], v[200:203], v[152:155], v[96:99]
	v_mfma_f32_16x16x32_bf16 v[88:91], v[188:191], v[160:163], v[88:91]
	v_mfma_f32_16x16x32_bf16 v[80:83], v[200:203], v[160:163], v[80:83]
	v_mfma_f32_16x16x32_bf16 v[72:75], v[188:191], v[168:171], v[72:75]
	v_mfma_f32_16x16x32_bf16 v[64:67], v[200:203], v[168:171], v[64:67]
	v_mfma_f32_16x16x32_bf16 v[120:123], v[196:199], v[148:151], v[120:123]
	v_mfma_f32_16x16x32_bf16 v[112:115], v[218:221], v[148:151], v[112:115]
	v_mfma_f32_16x16x32_bf16 v[104:107], v[196:199], v[156:159], v[104:107]
	v_mfma_f32_16x16x32_bf16 v[96:99], v[218:221], v[156:159], v[96:99]
	v_mfma_f32_16x16x32_bf16 v[88:91], v[196:199], v[164:167], v[88:91]
	v_mfma_f32_16x16x32_bf16 v[80:83], v[218:221], v[164:167], v[80:83]
	v_mfma_f32_16x16x32_bf16 v[72:75], v[196:199], v[172:175], v[72:75]
	v_mfma_f32_16x16x32_bf16 v[64:67], v[218:221], v[172:175], v[64:67]
	s_add_u32 s76, s44, 0x80
	s_addc_u32 s77, s45, 0
	s_add_u32 s98, s44, 0x80080
	s_addc_u32 s99, s45, 0
	s_barrier
	ds_read_b128 v[144:147], v216 offset:49152
	ds_read_b128 v[148:151], v216 offset:50176
	ds_read_b128 v[152:155], v216 offset:51200
	ds_read_b128 v[156:159], v216 offset:52224
	s_add_i32 m0, s92, 0x18000
	ds_read_b128 v[160:163], v216 offset:53248
	ds_read_b128 v[164:167], v216 offset:54272
	ds_read_b128 v[168:171], v216 offset:55296
	ds_read_b128 v[172:175], v216 offset:56320
	global_load_lds_dwordx4 v192, s[76:77]
	s_add_i32 m0, s92, 0x1a000
	s_nop 0
	global_load_lds_dwordx4 v180, s[76:77]
	s_add_i32 m0, s92, 0x1c000
	s_nop 0
	global_load_lds_dwordx4 v192, s[98:99]
	s_add_i32 m0, s92, 0x1e000
	s_nop 0
	global_load_lds_dwordx4 v180, s[98:99]
	s_waitcnt vmcnt(4)
	s_waitcnt lgkmcnt(0)
	s_barrier
	v_mfma_f32_16x16x32_bf16 v[60:63], v[128:131], v[144:147], v[60:63]
	v_mfma_f32_16x16x32_bf16 v[52:55], v[136:139], v[144:147], v[52:55]
	v_mfma_f32_16x16x32_bf16 v[44:47], v[128:131], v[152:155], v[44:47]
	v_mfma_f32_16x16x32_bf16 v[36:39], v[136:139], v[152:155], v[36:39]
	v_mfma_f32_16x16x32_bf16 v[28:31], v[128:131], v[160:163], v[28:31]
	v_mfma_f32_16x16x32_bf16 v[20:23], v[136:139], v[160:163], v[20:23]
	v_mfma_f32_16x16x32_bf16 v[12:15], v[128:131], v[168:171], v[12:15]
	v_mfma_f32_16x16x32_bf16 v[4:7], v[136:139], v[168:171], v[4:7]
	v_mfma_f32_16x16x32_bf16 v[60:63], v[132:135], v[148:151], v[60:63]
	v_mfma_f32_16x16x32_bf16 v[52:55], v[140:143], v[148:151], v[52:55]
	v_mfma_f32_16x16x32_bf16 v[44:47], v[132:135], v[156:159], v[44:47]
	v_mfma_f32_16x16x32_bf16 v[36:39], v[140:143], v[156:159], v[36:39]
	v_mfma_f32_16x16x32_bf16 v[28:31], v[132:135], v[164:167], v[28:31]
	v_mfma_f32_16x16x32_bf16 v[20:23], v[140:143], v[164:167], v[20:23]
	v_mfma_f32_16x16x32_bf16 v[12:15], v[132:135], v[172:175], v[12:15]
	v_mfma_f32_16x16x32_bf16 v[4:7], v[140:143], v[172:175], v[4:7]
	v_mfma_f32_16x16x32_bf16 v[56:59], v[188:191], v[144:147], v[56:59]
	v_mfma_f32_16x16x32_bf16 v[48:51], v[200:203], v[144:147], v[48:51]
	v_mfma_f32_16x16x32_bf16 v[40:43], v[188:191], v[152:155], v[40:43]
	v_mfma_f32_16x16x32_bf16 v[32:35], v[200:203], v[152:155], v[32:35]
	v_mfma_f32_16x16x32_bf16 v[24:27], v[188:191], v[160:163], v[24:27]
	v_mfma_f32_16x16x32_bf16 v[16:19], v[200:203], v[160:163], v[16:19]
	v_mfma_f32_16x16x32_bf16 v[8:11], v[188:191], v[168:171], v[8:11]
	v_mfma_f32_16x16x32_bf16 v[0:3], v[200:203], v[168:171], v[0:3]
	v_mfma_f32_16x16x32_bf16 v[56:59], v[196:199], v[148:151], v[56:59]
	v_mfma_f32_16x16x32_bf16 v[48:51], v[218:221], v[148:151], v[48:51]
	v_mfma_f32_16x16x32_bf16 v[40:43], v[196:199], v[156:159], v[40:43]
	v_mfma_f32_16x16x32_bf16 v[32:35], v[218:221], v[156:159], v[32:35]
	v_mfma_f32_16x16x32_bf16 v[24:27], v[196:199], v[164:167], v[24:27]
	v_mfma_f32_16x16x32_bf16 v[16:19], v[218:221], v[164:167], v[16:19]
	v_mfma_f32_16x16x32_bf16 v[8:11], v[196:199], v[172:175], v[8:11]
	v_mfma_f32_16x16x32_bf16 v[0:3], v[218:221], v[172:175], v[0:3]
	s_add_i32 s69, s69, 2
	s_add_u32 s40, s40, 0x100
	s_addc_u32 s41, s41, 0
	s_add_u32 s9, s9, 0x100
	s_addc_u32 s15, s15, 0
	s_add_u32 s44, s40, 0xfff80080
	s_addc_u32 s45, s41, -1
	s_cmp_eq_u32 s69, 28
	s_cselect_b32 s47, s5, s45
	s_cselect_b32 s46, s4, s44
	s_cselect_b32 s45, s13, s15
	s_cselect_b32 s44, s12, s9
	s_add_u32 s76, s40, 0xfff80000
	s_addc_u32 s77, s41, -1
	s_cmp_gt_u32 s69, 29
	s_barrier
	.p2align 6
; #define PG8_STAGE(bufoff, gbase, voff) do { _Pragma("unroll") for (int _i = 0; _i < 2; ++_i) \
;         __builtin_amdgcn_global_load_lds((const unsigned*)((const char*)(gbase) + (voff)[_i]), (LAS unsigned*)(lds + (bufoff) + ldsw + _i * 8192), 16, 0, 0); } while (0)
; #define PG8_LDA(dst, b, h) do { _Pragma("unroll") for (int m = 0; m < 4; ++m) _Pragma("unroll") for (int k = 0; k < 2; ++k) dst[m][k] = *(const LAS bf16x8*)(lds + PG8_SA(b, h) + aoff + m * 2048 + k * 1024); } while (0)
; #define PG8_LDB(dst, b, h) do { _Pragma("unroll") for (int n = 0; n < 2; ++n) _Pragma("unroll") for (int k = 0; k < 2; ++k) dst[n][k] = *(const LAS bf16x8*)(lds + PG8_SB(b, h) + boff + n * 2048 + k * 1024); } while (0)
; #define PG8_MMA(ai, bj, At, Bt) do { __builtin_amdgcn_s_setprio(1); _Pragma("unroll") for (int m = 0; m < 4; ++m) _Pragma("unroll") for (int n = 0; n < 2; ++n) _Pragma("unroll") for (int k = 0; k < 2; ++k) \
;         acc[ai][bj][m][n] = __builtin_amdgcn_mfma_f32_16x16x32_bf16(Bt[n][k], At[m][k], acc[ai][bj][m][n], 0, 0, 0); __builtin_amdgcn_s_setprio(0); } while (0)
; #define PG8_WAIT_V(n) asm volatile("s_waitcnt vmcnt(" #n ")" ::: "memory")
; #define PG8_WAIT_L(n) asm volatile("s_waitcnt lgkmcnt(" #n ")" ::: "memory")
; #define PG8_BAR __builtin_amdgcn_s_barrier()
; #define PG8_SCHED __builtin_amdgcn_sched_barrier(0)
; template <class Prog>
; __device__ __forceinline__ void gemm_phase(LAS unsigned char* lds, const int K, const Prog& S) {
;     ...
;             PG8_LDB(B0, 0, 0); PG8_SCHED; PG8_LDA(At, 0, 0); PG8_STAGE(PG8_SA(1, 1), a1 + hstep, voffA);
;             PG8_WAIT_L(8); PG8_BAR; PG8_WAIT_L(0); PG8_MMA(0, 0, At, B0); PG8_BAR; PG8_SCHED;
;             PG8_LDB(B1, 0, 1); PG8_STAGE(PG8_SB(0, 0), b2, voffB);
;             PG8_BAR; PG8_WAIT_L(0); PG8_MMA(0, 1, At, B1); PG8_BAR;
;             PG8_LDA(At, 0, 1); PG8_STAGE(PG8_SA(0, 0), a2, voffA);
;             PG8_BAR; PG8_WAIT_L(0); PG8_MMA(1, 0, At, B0); PG8_BAR; PG8_SCHED;
;             PG8_STAGE(PG8_SB(0, 1), b2 + hstep, voffB);
;             PG8_WAIT_V(6); PG8_BAR; PG8_MMA(1, 1, At, B1); PG8_BAR;
.LBB0_101:
	ds_read_b128 v[128:131], v244
	ds_read_b128 v[132:135], v244 offset:1024
	ds_read_b128 v[136:139], v244 offset:2048
	ds_read_b128 v[140:143], v244 offset:3072
	s_add_i32 m0, s92, 0x8000
	ds_read_b128 v[188:191], v244 offset:16384
	ds_read_b128 v[196:199], v244 offset:17408
	ds_read_b128 v[200:203], v244 offset:18432
	ds_read_b128 v[218:221], v244 offset:19456
	global_load_lds_dwordx4 v184, s[76:77]
	s_add_i32 m0, s92, 0xa000
	ds_read_b128 v[144:147], v216
	ds_read_b128 v[148:151], v216 offset:1024
	ds_read_b128 v[152:155], v216 offset:2048
	ds_read_b128 v[156:159], v216 offset:3072
	global_load_lds_dwordx4 v186, s[76:77]
	s_add_i32 m0, s92, 0xc000
	ds_read_b128 v[160:163], v216 offset:4096
	ds_read_b128 v[164:167], v216 offset:5120
	ds_read_b128 v[168:171], v216 offset:6144
	ds_read_b128 v[172:175], v216 offset:7168
	global_load_lds_dwordx4 v184, s[40:41]
	s_add_i32 m0, s92, 0xe000
	s_nop 0
	global_load_lds_dwordx4 v186, s[40:41]
	s_waitcnt lgkmcnt(0)
	s_barrier
	v_mfma_f32_16x16x32_bf16 v[124:127], v[128:131], v[144:147], v[124:127]
	v_mfma_f32_16x16x32_bf16 v[116:119], v[136:139], v[144:147], v[116:119]
	v_mfma_f32_16x16x32_bf16 v[108:111], v[128:131], v[152:155], v[108:111]
	v_mfma_f32_16x16x32_bf16 v[100:103], v[136:139], v[152:155], v[100:103]
	v_mfma_f32_16x16x32_bf16 v[92:95], v[128:131], v[160:163], v[92:95]
	v_mfma_f32_16x16x32_bf16 v[84:87], v[136:139], v[160:163], v[84:87]
	v_mfma_f32_16x16x32_bf16 v[76:79], v[128:131], v[168:171], v[76:79]
	v_mfma_f32_16x16x32_bf16 v[68:71], v[136:139], v[168:171], v[68:71]
	v_mfma_f32_16x16x32_bf16 v[124:127], v[132:135], v[148:151], v[124:127]
	v_mfma_f32_16x16x32_bf16 v[116:119], v[140:143], v[148:151], v[116:119]
	v_mfma_f32_16x16x32_bf16 v[108:111], v[132:135], v[156:159], v[108:111]
	v_mfma_f32_16x16x32_bf16 v[100:103], v[140:143], v[156:159], v[100:103]
	v_mfma_f32_16x16x32_bf16 v[92:95], v[132:135], v[164:167], v[92:95]
	v_mfma_f32_16x16x32_bf16 v[84:87], v[140:143], v[164:167], v[84:87]
	v_mfma_f32_16x16x32_bf16 v[76:79], v[132:135], v[172:175], v[76:79]
	v_mfma_f32_16x16x32_bf16 v[68:71], v[140:143], v[172:175], v[68:71]
	v_mfma_f32_16x16x32_bf16 v[120:123], v[188:191], v[144:147], v[120:123]
	v_mfma_f32_16x16x32_bf16 v[112:115], v[200:203], v[144:147], v[112:115]
	v_mfma_f32_16x16x32_bf16 v[104:107], v[188:191], v[152:155], v[104:107]
	v_mfma_f32_16x16x32_bf16 v[96:99], v[200:203], v[152:155], v[96:99]
	v_mfma_f32_16x16x32_bf16 v[88:91], v[188:191], v[160:163], v[88:91]
	v_mfma_f32_16x16x32_bf16 v[80:83], v[200:203], v[160:163], v[80:83]
	v_mfma_f32_16x16x32_bf16 v[72:75], v[188:191], v[168:171], v[72:75]
	v_mfma_f32_16x16x32_bf16 v[64:67], v[200:203], v[168:171], v[64:67]
	v_mfma_f32_16x16x32_bf16 v[120:123], v[196:199], v[148:151], v[120:123]
	v_mfma_f32_16x16x32_bf16 v[112:115], v[218:221], v[148:151], v[112:115]
	v_mfma_f32_16x16x32_bf16 v[104:107], v[196:199], v[156:159], v[104:107]
	v_mfma_f32_16x16x32_bf16 v[96:99], v[218:221], v[156:159], v[96:99]
	v_mfma_f32_16x16x32_bf16 v[88:91], v[196:199], v[164:167], v[88:91]
	v_mfma_f32_16x16x32_bf16 v[80:83], v[218:221], v[164:167], v[80:83]
	v_mfma_f32_16x16x32_bf16 v[72:75], v[196:199], v[172:175], v[72:75]
	v_mfma_f32_16x16x32_bf16 v[64:67], v[218:221], v[172:175], v[64:67]
	s_add_u32 s76, s44, 0x80000
	s_addc_u32 s77, s45, 0
	s_barrier
	ds_read_b128 v[144:147], v216 offset:16384
	ds_read_b128 v[148:151], v216 offset:17408
	ds_read_b128 v[152:155], v216 offset:18432
	ds_read_b128 v[156:159], v216 offset:19456
	s_add_i32 m0, s92, 0x10000
	ds_read_b128 v[160:163], v216 offset:20480
	ds_read_b128 v[164:167], v216 offset:21504
	ds_read_b128 v[168:171], v216 offset:22528
	ds_read_b128 v[172:175], v216 offset:23552
	global_load_lds_dwordx4 v192, s[44:45]
	s_add_i32 m0, s92, 0x12000
	s_nop 0
	global_load_lds_dwordx4 v180, s[44:45]
	s_add_i32 m0, s92, 0x14000
	s_nop 0
	global_load_lds_dwordx4 v192, s[76:77]
	s_add_i32 m0, s92, 0x16000
	s_nop 0
	global_load_lds_dwordx4 v180, s[76:77]
	s_waitcnt vmcnt(4)
	s_waitcnt lgkmcnt(0)
	s_barrier
	v_mfma_f32_16x16x32_bf16 v[60:63], v[128:131], v[144:147], v[60:63]
	v_mfma_f32_16x16x32_bf16 v[52:55], v[136:139], v[144:147], v[52:55]
	v_mfma_f32_16x16x32_bf16 v[44:47], v[128:131], v[152:155], v[44:47]
	v_mfma_f32_16x16x32_bf16 v[36:39], v[136:139], v[152:155], v[36:39]
	v_mfma_f32_16x16x32_bf16 v[28:31], v[128:131], v[160:163], v[28:31]
	v_mfma_f32_16x16x32_bf16 v[20:23], v[136:139], v[160:163], v[20:23]
	v_mfma_f32_16x16x32_bf16 v[12:15], v[128:131], v[168:171], v[12:15]
	v_mfma_f32_16x16x32_bf16 v[4:7], v[136:139], v[168:171], v[4:7]
	v_mfma_f32_16x16x32_bf16 v[60:63], v[132:135], v[148:151], v[60:63]
	v_mfma_f32_16x16x32_bf16 v[52:55], v[140:143], v[148:151], v[52:55]
	v_mfma_f32_16x16x32_bf16 v[44:47], v[132:135], v[156:159], v[44:47]
	v_mfma_f32_16x16x32_bf16 v[36:39], v[140:143], v[156:159], v[36:39]
	v_mfma_f32_16x16x32_bf16 v[28:31], v[132:135], v[164:167], v[28:31]
	v_mfma_f32_16x16x32_bf16 v[20:23], v[140:143], v[164:167], v[20:23]
	v_mfma_f32_16x16x32_bf16 v[12:15], v[132:135], v[172:175], v[12:15]
	v_mfma_f32_16x16x32_bf16 v[4:7], v[140:143], v[172:175], v[4:7]
	v_mfma_f32_16x16x32_bf16 v[56:59], v[188:191], v[144:147], v[56:59]
	v_mfma_f32_16x16x32_bf16 v[48:51], v[200:203], v[144:147], v[48:51]
	v_mfma_f32_16x16x32_bf16 v[40:43], v[188:191], v[152:155], v[40:43]
	v_mfma_f32_16x16x32_bf16 v[32:35], v[200:203], v[152:155], v[32:35]
	v_mfma_f32_16x16x32_bf16 v[24:27], v[188:191], v[160:163], v[24:27]
	v_mfma_f32_16x16x32_bf16 v[16:19], v[200:203], v[160:163], v[16:19]
	v_mfma_f32_16x16x32_bf16 v[8:11], v[188:191], v[168:171], v[8:11]
	v_mfma_f32_16x16x32_bf16 v[0:3], v[200:203], v[168:171], v[0:3]
	v_mfma_f32_16x16x32_bf16 v[56:59], v[196:199], v[148:151], v[56:59]
	v_mfma_f32_16x16x32_bf16 v[48:51], v[218:221], v[148:151], v[48:51]
	v_mfma_f32_16x16x32_bf16 v[40:43], v[196:199], v[156:159], v[40:43]
	v_mfma_f32_16x16x32_bf16 v[32:35], v[218:221], v[156:159], v[32:35]
	v_mfma_f32_16x16x32_bf16 v[24:27], v[196:199], v[164:167], v[24:27]
	v_mfma_f32_16x16x32_bf16 v[16:19], v[218:221], v[164:167], v[16:19]
	v_mfma_f32_16x16x32_bf16 v[8:11], v[196:199], v[172:175], v[8:11]
	v_mfma_f32_16x16x32_bf16 v[0:3], v[218:221], v[172:175], v[0:3]
	s_add_u32 s76, s46, 0x80000
	s_addc_u32 s77, s47, 0
	s_barrier
; #define PG8_STAGE(bufoff, gbase, voff) do { _Pragma("unroll") for (int _i = 0; _i < 2; ++_i) \
;         __builtin_amdgcn_global_load_lds((const unsigned*)((const char*)(gbase) + (voff)[_i]), (LAS unsigned*)(lds + (bufoff) + ldsw + _i * 8192), 16, 0, 0); } while (0)
; #define PG8_LDA(dst, b, h) do { _Pragma("unroll") for (int m = 0; m < 4; ++m) _Pragma("unroll") for (int k = 0; k < 2; ++k) dst[m][k] = *(const LAS bf16x8*)(lds + PG8_SA(b, h) + aoff + m * 2048 + k * 1024); } while (0)
; #define PG8_LDB(dst, b, h) do { _Pragma("unroll") for (int n = 0; n < 2; ++n) _Pragma("unroll") for (int k = 0; k < 2; ++k) dst[n][k] = *(const LAS bf16x8*)(lds + PG8_SB(b, h) + boff + n * 2048 + k * 1024); } while (0)
; #define PG8_MMA(ai, bj, At, Bt) do { __builtin_amdgcn_s_setprio(1); _Pragma("unroll") for (int m = 0; m < 4; ++m) _Pragma("unroll") for (int n = 0; n < 2; ++n) _Pragma("unroll") for (int k = 0; k < 2; ++k) \
;         acc[ai][bj][m][n] = __builtin_amdgcn_mfma_f32_16x16x32_bf16(Bt[n][k], At[m][k], acc[ai][bj][m][n], 0, 0, 0); __builtin_amdgcn_s_setprio(0); } while (0)
; #define PG8_BAR __builtin_amdgcn_s_barrier()
; template <class Prog>
; __device__ __forceinline__ void gemm_phase(LAS unsigned char* lds, const int K, const Prog& S) {
;     ...
;         const bool has_next = S.next(ui + 1, nxt);
;         const char* nA = has_next ? nxt.a : cA; const char* nB = has_next ? nxt.b : cB;
;         for (int t = 0; t < nt; t += 2) {
;             const bool last = (t == nt - 2);
;             const char* a1 = cA + (size_t)(t + 1) * kstep;
;             const char* a2 = last ? nA : cA + (size_t)(t + 2) * kstep; const char* b2 = last ? nB : cB + (size_t)(t + 2) * kstep;
;             const char* a3 = a2 + kstep; const char* b3 = b2 + kstep;
;     ...
;             PG8_LDB(B0, 1, 0); PG8_SCHED; PG8_LDA(At, 1, 0); PG8_STAGE(PG8_SA(0, 1), a2 + hstep, voffA);
;             PG8_WAIT_L(8); PG8_BAR; PG8_WAIT_L(0); PG8_MMA(0, 0, At, B0); PG8_BAR; PG8_SCHED;
;             PG8_LDB(B1, 1, 1); PG8_STAGE(PG8_SB(1, 0), b3, voffB);
;             PG8_BAR; PG8_WAIT_L(0); PG8_MMA(0, 1, At, B1); PG8_BAR;
;             PG8_LDA(At, 1, 1); PG8_STAGE(PG8_SA(1, 0), a3, voffA);
;             PG8_BAR; PG8_WAIT_L(0); PG8_MMA(1, 0, At, B0); PG8_BAR; PG8_SCHED;
;             PG8_STAGE(PG8_SB(1, 1), b3 + hstep, voffB);
;             PG8_WAIT_V(6); PG8_BAR; PG8_MMA(1, 1, At, B1); PG8_BAR;
	ds_read_b128 v[128:131], v244 offset:32768
	ds_read_b128 v[132:135], v244 offset:33792
	ds_read_b128 v[136:139], v244 offset:34816
	ds_read_b128 v[140:143], v244 offset:35840
	s_mov_b32 m0, s92
	ds_read_b128 v[188:191], v244 offset:49152
	ds_read_b128 v[196:199], v244 offset:50176
	ds_read_b128 v[200:203], v244 offset:51200
	ds_read_b128 v[218:221], v244 offset:52224
	global_load_lds_dwordx4 v176, s[46:47]
	s_add_i32 m0, s92, 0x2000
	ds_read_b128 v[144:147], v216 offset:32768
	ds_read_b128 v[148:151], v216 offset:33792
	ds_read_b128 v[152:155], v216 offset:34816
	ds_read_b128 v[156:159], v216 offset:35840
	global_load_lds_dwordx4 v178, s[46:47]
	s_add_i32 m0, s92, 0x4000
	ds_read_b128 v[160:163], v216 offset:36864
	ds_read_b128 v[164:167], v216 offset:37888
	ds_read_b128 v[168:171], v216 offset:38912
	ds_read_b128 v[172:175], v216 offset:39936
	global_load_lds_dwordx4 v176, s[76:77]
	s_add_i32 m0, s92, 0x6000
	s_nop 0
	global_load_lds_dwordx4 v178, s[76:77]
	s_waitcnt lgkmcnt(0)
	s_barrier
	v_mfma_f32_16x16x32_bf16 v[124:127], v[128:131], v[144:147], v[124:127]
	v_mfma_f32_16x16x32_bf16 v[116:119], v[136:139], v[144:147], v[116:119]
	v_mfma_f32_16x16x32_bf16 v[108:111], v[128:131], v[152:155], v[108:111]
	v_mfma_f32_16x16x32_bf16 v[100:103], v[136:139], v[152:155], v[100:103]
	v_mfma_f32_16x16x32_bf16 v[92:95], v[128:131], v[160:163], v[92:95]
	v_mfma_f32_16x16x32_bf16 v[84:87], v[136:139], v[160:163], v[84:87]
	v_mfma_f32_16x16x32_bf16 v[76:79], v[128:131], v[168:171], v[76:79]
	v_mfma_f32_16x16x32_bf16 v[68:71], v[136:139], v[168:171], v[68:71]
	v_mfma_f32_16x16x32_bf16 v[124:127], v[132:135], v[148:151], v[124:127]
	v_mfma_f32_16x16x32_bf16 v[116:119], v[140:143], v[148:151], v[116:119]
	v_mfma_f32_16x16x32_bf16 v[108:111], v[132:135], v[156:159], v[108:111]
	v_mfma_f32_16x16x32_bf16 v[100:103], v[140:143], v[156:159], v[100:103]
	v_mfma_f32_16x16x32_bf16 v[92:95], v[132:135], v[164:167], v[92:95]
	v_mfma_f32_16x16x32_bf16 v[84:87], v[140:143], v[164:167], v[84:87]
	v_mfma_f32_16x16x32_bf16 v[76:79], v[132:135], v[172:175], v[76:79]
	v_mfma_f32_16x16x32_bf16 v[68:71], v[140:143], v[172:175], v[68:71]
	v_mfma_f32_16x16x32_bf16 v[120:123], v[188:191], v[144:147], v[120:123]
	v_mfma_f32_16x16x32_bf16 v[112:115], v[200:203], v[144:147], v[112:115]
	v_mfma_f32_16x16x32_bf16 v[104:107], v[188:191], v[152:155], v[104:107]
	v_mfma_f32_16x16x32_bf16 v[96:99], v[200:203], v[152:155], v[96:99]
	v_mfma_f32_16x16x32_bf16 v[88:91], v[188:191], v[160:163], v[88:91]
	v_mfma_f32_16x16x32_bf16 v[80:83], v[200:203], v[160:163], v[80:83]
	v_mfma_f32_16x16x32_bf16 v[72:75], v[188:191], v[168:171], v[72:75]
	v_mfma_f32_16x16x32_bf16 v[64:67], v[200:203], v[168:171], v[64:67]
	v_mfma_f32_16x16x32_bf16 v[120:123], v[196:199], v[148:151], v[120:123]
	v_mfma_f32_16x16x32_bf16 v[112:115], v[218:221], v[148:151], v[112:115]
	v_mfma_f32_16x16x32_bf16 v[104:107], v[196:199], v[156:159], v[104:107]
	v_mfma_f32_16x16x32_bf16 v[96:99], v[218:221], v[156:159], v[96:99]
	v_mfma_f32_16x16x32_bf16 v[88:91], v[196:199], v[164:167], v[88:91]
	v_mfma_f32_16x16x32_bf16 v[80:83], v[218:221], v[164:167], v[80:83]
	v_mfma_f32_16x16x32_bf16 v[72:75], v[196:199], v[172:175], v[72:75]
	v_mfma_f32_16x16x32_bf16 v[64:67], v[218:221], v[172:175], v[64:67]
	s_add_u32 s76, s44, 0x80
	s_addc_u32 s77, s45, 0
	s_add_u32 s98, s44, 0x80080
	s_addc_u32 s99, s45, 0
	s_barrier
	ds_read_b128 v[144:147], v216 offset:49152
	ds_read_b128 v[148:151], v216 offset:50176
	ds_read_b128 v[152:155], v216 offset:51200
	ds_read_b128 v[156:159], v216 offset:52224
	s_add_i32 m0, s92, 0x18000
	ds_read_b128 v[160:163], v216 offset:53248
	ds_read_b128 v[164:167], v216 offset:54272
	ds_read_b128 v[168:171], v216 offset:55296
	ds_read_b128 v[172:175], v216 offset:56320
	global_load_lds_dwordx4 v192, s[76:77]
	s_add_i32 m0, s92, 0x1a000
	s_nop 0
	global_load_lds_dwordx4 v180, s[76:77]
	s_add_i32 m0, s92, 0x1c000
	s_nop 0
	global_load_lds_dwordx4 v192, s[98:99]
	s_add_i32 m0, s92, 0x1e000
	s_nop 0
	global_load_lds_dwordx4 v180, s[98:99]
	s_waitcnt vmcnt(4)
	s_waitcnt lgkmcnt(0)
	s_barrier
	v_mfma_f32_16x16x32_bf16 v[60:63], v[128:131], v[144:147], v[60:63]
	v_mfma_f32_16x16x32_bf16 v[52:55], v[136:139], v[144:147], v[52:55]
	v_mfma_f32_16x16x32_bf16 v[44:47], v[128:131], v[152:155], v[44:47]
	v_mfma_f32_16x16x32_bf16 v[36:39], v[136:139], v[152:155], v[36:39]
	v_mfma_f32_16x16x32_bf16 v[28:31], v[128:131], v[160:163], v[28:31]
	v_mfma_f32_16x16x32_bf16 v[20:23], v[136:139], v[160:163], v[20:23]
	v_mfma_f32_16x16x32_bf16 v[12:15], v[128:131], v[168:171], v[12:15]
	v_mfma_f32_16x16x32_bf16 v[4:7], v[136:139], v[168:171], v[4:7]
	v_mfma_f32_16x16x32_bf16 v[60:63], v[132:135], v[148:151], v[60:63]
	v_mfma_f32_16x16x32_bf16 v[52:55], v[140:143], v[148:151], v[52:55]
	v_mfma_f32_16x16x32_bf16 v[44:47], v[132:135], v[156:159], v[44:47]
	v_mfma_f32_16x16x32_bf16 v[36:39], v[140:143], v[156:159], v[36:39]
	v_mfma_f32_16x16x32_bf16 v[28:31], v[132:135], v[164:167], v[28:31]
	v_mfma_f32_16x16x32_bf16 v[20:23], v[140:143], v[164:167], v[20:23]
	v_mfma_f32_16x16x32_bf16 v[12:15], v[132:135], v[172:175], v[12:15]
	v_mfma_f32_16x16x32_bf16 v[4:7], v[140:143], v[172:175], v[4:7]
	v_mfma_f32_16x16x32_bf16 v[56:59], v[188:191], v[144:147], v[56:59]
	v_mfma_f32_16x16x32_bf16 v[48:51], v[200:203], v[144:147], v[48:51]
	v_mfma_f32_16x16x32_bf16 v[40:43], v[188:191], v[152:155], v[40:43]
	v_mfma_f32_16x16x32_bf16 v[32:35], v[200:203], v[152:155], v[32:35]
	v_mfma_f32_16x16x32_bf16 v[24:27], v[188:191], v[160:163], v[24:27]
	v_mfma_f32_16x16x32_bf16 v[16:19], v[200:203], v[160:163], v[16:19]
	v_mfma_f32_16x16x32_bf16 v[8:11], v[188:191], v[168:171], v[8:11]
	v_mfma_f32_16x16x32_bf16 v[0:3], v[200:203], v[168:171], v[0:3]
	v_mfma_f32_16x16x32_bf16 v[56:59], v[196:199], v[148:151], v[56:59]
	v_mfma_f32_16x16x32_bf16 v[48:51], v[218:221], v[148:151], v[48:51]
	v_mfma_f32_16x16x32_bf16 v[40:43], v[196:199], v[156:159], v[40:43]
	v_mfma_f32_16x16x32_bf16 v[32:35], v[218:221], v[156:159], v[32:35]
	v_mfma_f32_16x16x32_bf16 v[24:27], v[196:199], v[164:167], v[24:27]
	v_mfma_f32_16x16x32_bf16 v[16:19], v[218:221], v[164:167], v[16:19]
	v_mfma_f32_16x16x32_bf16 v[8:11], v[196:199], v[172:175], v[8:11]
	v_mfma_f32_16x16x32_bf16 v[0:3], v[218:221], v[172:175], v[0:3]
	s_add_i32 s69, s69, 2
	s_add_u32 s40, s40, 0x100
	s_addc_u32 s41, s41, 0
	s_add_u32 s9, s9, 0x100
	s_addc_u32 s15, s15, 0
	s_add_u32 s44, s40, 0xfff80080
	s_addc_u32 s45, s41, -1
	s_cmp_eq_u32 s69, 28
	s_cselect_b32 s47, s5, s45
	s_cselect_b32 s46, s4, s44
	s_cselect_b32 s45, s13, s15
	s_cselect_b32 s44, s12, s9
	s_add_u32 s76, s40, 0xfff80000
	s_addc_u32 s77, s41, -1
	s_cmp_gt_u32 s69, 29
	s_barrier
	s_cbranch_scc0 .LBB0_101
	s_cmp_lt_i32 s75, 8
	s_mov_b32 s9, 1
	s_cbranch_scc1 .LBB0_110
	s_sub_i32 s4, s75, 30
	s_cmp_lt_u32 s4, 4
	s_mov_b32 s9, 2
	s_cbranch_scc1 .LBB0_110
	s_and_b32 s9, s75, 0x7ffffffc
	s_cmp_lt_i32 s9, 20
	s_cbranch_scc1 .LBB0_106
	s_cmp_lg_u32 s9, 20
	s_cselect_b64 s[4:5], -1, 0
	s_cbranch_execz .LBB0_107
	s_branch .LBB0_108

; #define PG8_STAGE(bufoff, gbase, voff) do { _Pragma("unroll") for (int _i = 0; _i < 2; ++_i) \
;         __builtin_amdgcn_global_load_lds((const unsigned*)((const char*)(gbase) + (voff)[_i]), (LAS unsigned*)(lds + (bufoff) + ldsw + _i * 8192), 16, 0, 0); } while (0)
; #define PG8_LDA(dst, b, h) do { _Pragma("unroll") for (int m = 0; m < 4; ++m) _Pragma("unroll") for (int k = 0; k < 2; ++k) dst[m][k] = *(const LAS bf16x8*)(lds + PG8_SA(b, h) + aoff + m * 2048 + k * 1024); } while (0)
; template <class Prog>
; __device__ __forceinline__ void gemm_phase(LAS unsigned char* lds, const int K, const Prog& S) {
;     ...
;     for (;;) {
;         const bool has_next = S.next(ui + 1, nxt);
;         const char* nA = has_next ? nxt.a : cA; const char* nB = has_next ? nxt.b : cB;
;         for (int t = 0; t < nt; t += 2) {
;             const bool last = (t == nt - 2);
;             const char* a1 = cA + (size_t)(t + 1) * kstep;
;             const char* a2 = last ? nA : cA + (size_t)(t + 2) * kstep; const char* b2 = last ? nB : cB + (size_t)(t + 2) * kstep;
;             const char* a3 = a2 + kstep; const char* b3 = b2 + kstep;
;             PG8_LDB(B0, 0, 0); PG8_SCHED; PG8_LDA(At, 0, 0); PG8_STAGE(PG8_SA(1, 1), a1 + hstep, voffA);
;             PG8_WAIT_L(8); PG8_BAR; PG8_WAIT_L(0); PG8_MMA(0, 0, At, B0); PG8_BAR; PG8_SCHED;
;             PG8_LDB(B1, 0, 1); PG8_STAGE(PG8_SB(0, 0), b2, voffB);
;             PG8_BAR; PG8_WAIT_L(0); PG8_MMA(0, 1, At, B1); PG8_BAR;
;             PG8_LDA(At, 0, 1); PG8_STAGE(PG8_SA(0, 0), a2, voffA);
;             PG8_BAR; PG8_WAIT_L(0); PG8_MMA(1, 0, At, B0); PG8_BAR; PG8_SCHED;
;             PG8_STAGE(PG8_SB(0, 1), b2 + hstep, voffB);
;             PG8_WAIT_V(6); PG8_BAR; PG8_MMA(1, 1, At, B1); PG8_BAR;
;             PG8_LDB(B0, 1, 0); PG8_SCHED; PG8_LDA(At, 1, 0); PG8_STAGE(PG8_SA(0, 1), a2 + hstep, voffA);
;             PG8_WAIT_L(8); PG8_BAR; PG8_WAIT_L(0); PG8_MMA(0, 0, At, B0); PG8_BAR; PG8_SCHED;
;             PG8_LDB(B1, 1, 1); PG8_STAGE(PG8_SB(1, 0), b3, voffB);
;             PG8_BAR; PG8_WAIT_L(0); PG8_MMA(0, 1, At, B1); PG8_BAR;
;             PG8_LDA(At, 1, 1); PG8_STAGE(PG8_SA(1, 0), a3, voffA);
;             PG8_BAR; PG8_WAIT_L(0); PG8_MMA(1, 0, At, B0); PG8_BAR; PG8_SCHED;
;             PG8_STAGE(PG8_SB(1, 1), b3 + hstep, voffB);
;             PG8_WAIT_V(6); PG8_BAR; PG8_MMA(1, 1, At, B1); PG8_BAR;
.LBB0_399:
	s_add_u32 s44, s44, 0x40080
	s_addc_u32 s45, s45, 0
	s_add_u32 s41, s46, 0x100
	s_addc_u32 s43, s47, 0
	s_mov_b32 s55, -2
	v_add_u32_e32 v206, 0x10000, v245
	s_add_u32 s46, s44, 0xfffc0080
	s_addc_u32 s47, s45, -1
	s_cmp_eq_u32 s55, 12
	s_cselect_b32 s53, s7, s47
	s_cselect_b32 s52, s6, s46
	s_cselect_b32 s47, s9, s43
	s_cselect_b32 s46, s8, s41
	s_add_u32 s84, s44, 0xfffc0000
	s_addc_u32 s85, s45, -1
	.p2align 6
.LBB0_400:
	ds_read_b128 v[128:131], v206
	ds_read_b128 v[132:135], v206 offset:1024
	ds_read_b128 v[136:139], v206 offset:2048
	ds_read_b128 v[140:143], v206 offset:3072
	s_add_i32 m0, s74, 0x8000
	ds_read_b128 v[176:179], v206 offset:16384
	ds_read_b128 v[180:183], v206 offset:17408
	ds_read_b128 v[184:187], v206 offset:18432
	ds_read_b128 v[188:191], v206 offset:19456
	global_load_lds_dwordx4 v202, s[84:85]
	s_add_i32 m0, s74, 0xa000
	ds_read_b128 v[144:147], v247
	ds_read_b128 v[148:151], v247 offset:1024
	ds_read_b128 v[152:155], v247 offset:2048
	ds_read_b128 v[156:159], v247 offset:3072
	global_load_lds_dwordx4 v204, s[84:85]
	s_add_i32 m0, s74, 0xc000
	ds_read_b128 v[160:163], v247 offset:4096
	ds_read_b128 v[164:167], v247 offset:5120
	ds_read_b128 v[168:171], v247 offset:6144
	ds_read_b128 v[172:175], v247 offset:7168
	global_load_lds_dwordx4 v202, s[44:45]
	s_add_i32 m0, s74, 0xe000
	s_nop 0
	global_load_lds_dwordx4 v204, s[44:45]
	s_waitcnt lgkmcnt(0)
	s_barrier
	v_mfma_f32_16x16x32_bf16 v[124:127], v[128:131], v[144:147], v[124:127]
	v_mfma_f32_16x16x32_bf16 v[120:123], v[136:139], v[144:147], v[120:123]
	v_mfma_f32_16x16x32_bf16 v[116:119], v[128:131], v[152:155], v[116:119]
	v_mfma_f32_16x16x32_bf16 v[112:115], v[136:139], v[152:155], v[112:115]
	v_mfma_f32_16x16x32_bf16 v[108:111], v[128:131], v[160:163], v[108:111]
	v_mfma_f32_16x16x32_bf16 v[104:107], v[136:139], v[160:163], v[104:107]
	v_mfma_f32_16x16x32_bf16 v[100:103], v[128:131], v[168:171], v[100:103]
	v_mfma_f32_16x16x32_bf16 v[96:99], v[136:139], v[168:171], v[96:99]
	v_mfma_f32_16x16x32_bf16 v[124:127], v[132:135], v[148:151], v[124:127]
	v_mfma_f32_16x16x32_bf16 v[120:123], v[140:143], v[148:151], v[120:123]
	v_mfma_f32_16x16x32_bf16 v[116:119], v[132:135], v[156:159], v[116:119]
	v_mfma_f32_16x16x32_bf16 v[112:115], v[140:143], v[156:159], v[112:115]
	v_mfma_f32_16x16x32_bf16 v[108:111], v[132:135], v[164:167], v[108:111]
	v_mfma_f32_16x16x32_bf16 v[104:107], v[140:143], v[164:167], v[104:107]
	v_mfma_f32_16x16x32_bf16 v[100:103], v[132:135], v[172:175], v[100:103]
	v_mfma_f32_16x16x32_bf16 v[96:99], v[140:143], v[172:175], v[96:99]
	v_mfma_f32_16x16x32_bf16 v[92:95], v[176:179], v[144:147], v[92:95]
	v_mfma_f32_16x16x32_bf16 v[88:91], v[184:187], v[144:147], v[88:91]
	v_mfma_f32_16x16x32_bf16 v[84:87], v[176:179], v[152:155], v[84:87]
	v_mfma_f32_16x16x32_bf16 v[80:83], v[184:187], v[152:155], v[80:83]
	v_mfma_f32_16x16x32_bf16 v[76:79], v[176:179], v[160:163], v[76:79]
	v_mfma_f32_16x16x32_bf16 v[72:75], v[184:187], v[160:163], v[72:75]
	v_mfma_f32_16x16x32_bf16 v[68:71], v[176:179], v[168:171], v[68:71]
	v_mfma_f32_16x16x32_bf16 v[64:67], v[184:187], v[168:171], v[64:67]
	v_mfma_f32_16x16x32_bf16 v[92:95], v[180:183], v[148:151], v[92:95]
	v_mfma_f32_16x16x32_bf16 v[88:91], v[188:191], v[148:151], v[88:91]
	v_mfma_f32_16x16x32_bf16 v[84:87], v[180:183], v[156:159], v[84:87]
	v_mfma_f32_16x16x32_bf16 v[80:83], v[188:191], v[156:159], v[80:83]
	v_mfma_f32_16x16x32_bf16 v[76:79], v[180:183], v[164:167], v[76:79]
	v_mfma_f32_16x16x32_bf16 v[72:75], v[188:191], v[164:167], v[72:75]
	v_mfma_f32_16x16x32_bf16 v[68:71], v[180:183], v[172:175], v[68:71]
	v_mfma_f32_16x16x32_bf16 v[64:67], v[188:191], v[172:175], v[64:67]
	s_add_u32 s84, s46, 0x40000
	s_addc_u32 s85, s47, 0
	s_barrier
	ds_read_b128 v[144:147], v247 offset:16384
	ds_read_b128 v[148:151], v247 offset:17408
	ds_read_b128 v[152:155], v247 offset:18432
	ds_read_b128 v[156:159], v247 offset:19456
	s_add_i32 m0, s74, 0x10000
	ds_read_b128 v[160:163], v247 offset:20480
	ds_read_b128 v[164:167], v247 offset:21504
	ds_read_b128 v[168:171], v247 offset:22528
	ds_read_b128 v[172:175], v247 offset:23552
	global_load_lds_dwordx4 v192, s[46:47]
	s_add_i32 m0, s74, 0x12000
	s_nop 0
	global_load_lds_dwordx4 v200, s[46:47]
	s_add_i32 m0, s74, 0x14000
	s_nop 0
	global_load_lds_dwordx4 v192, s[84:85]
	s_add_i32 m0, s74, 0x16000
	s_nop 0
	global_load_lds_dwordx4 v200, s[84:85]
	s_waitcnt vmcnt(4)
	s_waitcnt lgkmcnt(0)
	s_barrier
	v_mfma_f32_16x16x32_bf16 v[60:63], v[128:131], v[144:147], v[60:63]
	v_mfma_f32_16x16x32_bf16 v[56:59], v[136:139], v[144:147], v[56:59]
	v_mfma_f32_16x16x32_bf16 v[52:55], v[128:131], v[152:155], v[52:55]
	v_mfma_f32_16x16x32_bf16 v[48:51], v[136:139], v[152:155], v[48:51]
	v_mfma_f32_16x16x32_bf16 v[44:47], v[128:131], v[160:163], v[44:47]
	v_mfma_f32_16x16x32_bf16 v[40:43], v[136:139], v[160:163], v[40:43]
	v_mfma_f32_16x16x32_bf16 v[36:39], v[128:131], v[168:171], v[36:39]
	v_mfma_f32_16x16x32_bf16 v[32:35], v[136:139], v[168:171], v[32:35]
	v_mfma_f32_16x16x32_bf16 v[60:63], v[132:135], v[148:151], v[60:63]
	v_mfma_f32_16x16x32_bf16 v[56:59], v[140:143], v[148:151], v[56:59]
	v_mfma_f32_16x16x32_bf16 v[52:55], v[132:135], v[156:159], v[52:55]
	v_mfma_f32_16x16x32_bf16 v[48:51], v[140:143], v[156:159], v[48:51]
	v_mfma_f32_16x16x32_bf16 v[44:47], v[132:135], v[164:167], v[44:47]
	v_mfma_f32_16x16x32_bf16 v[40:43], v[140:143], v[164:167], v[40:43]
	v_mfma_f32_16x16x32_bf16 v[36:39], v[132:135], v[172:175], v[36:39]
	v_mfma_f32_16x16x32_bf16 v[32:35], v[140:143], v[172:175], v[32:35]
	v_mfma_f32_16x16x32_bf16 v[28:31], v[176:179], v[144:147], v[28:31]
	v_mfma_f32_16x16x32_bf16 v[24:27], v[184:187], v[144:147], v[24:27]
	v_mfma_f32_16x16x32_bf16 v[20:23], v[176:179], v[152:155], v[20:23]
	v_mfma_f32_16x16x32_bf16 v[16:19], v[184:187], v[152:155], v[16:19]
	v_mfma_f32_16x16x32_bf16 v[12:15], v[176:179], v[160:163], v[12:15]
	v_mfma_f32_16x16x32_bf16 v[8:11], v[184:187], v[160:163], v[8:11]
	v_mfma_f32_16x16x32_bf16 v[4:7], v[176:179], v[168:171], v[4:7]
	v_mfma_f32_16x16x32_bf16 v[0:3], v[184:187], v[168:171], v[0:3]
	v_mfma_f32_16x16x32_bf16 v[28:31], v[180:183], v[148:151], v[28:31]
	v_mfma_f32_16x16x32_bf16 v[24:27], v[188:191], v[148:151], v[24:27]
	v_mfma_f32_16x16x32_bf16 v[20:23], v[180:183], v[156:159], v[20:23]
	v_mfma_f32_16x16x32_bf16 v[16:19], v[188:191], v[156:159], v[16:19]
	v_mfma_f32_16x16x32_bf16 v[12:15], v[180:183], v[164:167], v[12:15]
	v_mfma_f32_16x16x32_bf16 v[8:11], v[188:191], v[164:167], v[8:11]
	v_mfma_f32_16x16x32_bf16 v[4:7], v[180:183], v[172:175], v[4:7]
	v_mfma_f32_16x16x32_bf16 v[0:3], v[188:191], v[172:175], v[0:3]
	s_add_u32 s84, s52, 0x40000
	s_addc_u32 s85, s53, 0
	s_barrier
; #define PG8_STAGE(bufoff, gbase, voff) do { _Pragma("unroll") for (int _i = 0; _i < 2; ++_i) \
;         __builtin_amdgcn_global_load_lds((const unsigned*)((const char*)(gbase) + (voff)[_i]), (LAS unsigned*)(lds + (bufoff) + ldsw + _i * 8192), 16, 0, 0); } while (0)
; #define PG8_LDA(dst, b, h) do { _Pragma("unroll") for (int m = 0; m < 4; ++m) _Pragma("unroll") for (int k = 0; k < 2; ++k) dst[m][k] = *(const LAS bf16x8*)(lds + PG8_SA(b, h) + aoff + m * 2048 + k * 1024); } while (0)
; #define PG8_WAIT_V(n) asm volatile("s_waitcnt vmcnt(" #n ")" ::: "memory")
; #define PG8_WAIT_L(n) asm volatile("s_waitcnt lgkmcnt(" #n ")" ::: "memory")
; template <class Prog>
; __device__ __forceinline__ void gemm_phase(LAS unsigned char* lds, const int K, const Prog& S) {
;     ...
;         for (int t = 0; t < nt; t += 2) {
;             const bool last = (t == nt - 2);
;             const char* a1 = cA + (size_t)(t + 1) * kstep;
;             const char* a2 = last ? nA : cA + (size_t)(t + 2) * kstep; const char* b2 = last ? nB : cB + (size_t)(t + 2) * kstep;
;             const char* a3 = a2 + kstep; const char* b3 = b2 + kstep;
;             PG8_LDB(B0, 0, 0); PG8_SCHED; PG8_LDA(At, 0, 0); PG8_STAGE(PG8_SA(1, 1), a1 + hstep, voffA);
;             PG8_WAIT_L(8); PG8_BAR; PG8_WAIT_L(0); PG8_MMA(0, 0, At, B0); PG8_BAR; PG8_SCHED;
;             PG8_LDB(B1, 0, 1); PG8_STAGE(PG8_SB(0, 0), b2, voffB);
;             PG8_BAR; PG8_WAIT_L(0); PG8_MMA(0, 1, At, B1); PG8_BAR;
;             PG8_LDA(At, 0, 1); PG8_STAGE(PG8_SA(0, 0), a2, voffA);
;             PG8_BAR; PG8_WAIT_L(0); PG8_MMA(1, 0, At, B0); PG8_BAR; PG8_SCHED;
;             PG8_STAGE(PG8_SB(0, 1), b2 + hstep, voffB);
;             PG8_WAIT_V(6); PG8_BAR; PG8_MMA(1, 1, At, B1); PG8_BAR;
;             PG8_LDB(B0, 1, 0); PG8_SCHED; PG8_LDA(At, 1, 0); PG8_STAGE(PG8_SA(0, 1), a2 + hstep, voffA);
;             PG8_WAIT_L(8); PG8_BAR; PG8_WAIT_L(0); PG8_MMA(0, 0, At, B0); PG8_BAR; PG8_SCHED;
;             PG8_LDB(B1, 1, 1); PG8_STAGE(PG8_SB(1, 0), b3, voffB);
;             PG8_BAR; PG8_WAIT_L(0); PG8_MMA(0, 1, At, B1); PG8_BAR;
;             PG8_LDA(At, 1, 1); PG8_STAGE(PG8_SA(1, 0), a3, voffA);
;             PG8_BAR; PG8_WAIT_L(0); PG8_MMA(1, 0, At, B0); PG8_BAR; PG8_SCHED;
;             PG8_STAGE(PG8_SB(1, 1), b3 + hstep, voffB);
;             PG8_WAIT_V(6); PG8_BAR; PG8_MMA(1, 1, At, B1); PG8_BAR;
	ds_read_b128 v[128:131], v206 offset:32768
	ds_read_b128 v[132:135], v206 offset:33792
	ds_read_b128 v[136:139], v206 offset:34816
	ds_read_b128 v[140:143], v206 offset:35840
	s_mov_b32 m0, s74
	ds_read_b128 v[176:179], v206 offset:49152
	ds_read_b128 v[180:183], v206 offset:50176
	ds_read_b128 v[184:187], v206 offset:51200
	ds_read_b128 v[188:191], v206 offset:52224
	global_load_lds_dwordx4 v196, s[52:53]
	s_add_i32 m0, s74, 0x2000
	ds_read_b128 v[144:147], v247 offset:32768
	ds_read_b128 v[148:151], v247 offset:33792
	ds_read_b128 v[152:155], v247 offset:34816
	ds_read_b128 v[156:159], v247 offset:35840
	global_load_lds_dwordx4 v198, s[52:53]
	s_add_i32 m0, s74, 0x4000
	ds_read_b128 v[160:163], v247 offset:36864
	ds_read_b128 v[164:167], v247 offset:37888
	ds_read_b128 v[168:171], v247 offset:38912
	ds_read_b128 v[172:175], v247 offset:39936
	global_load_lds_dwordx4 v196, s[84:85]
	s_add_i32 m0, s74, 0x6000
	s_nop 0
	global_load_lds_dwordx4 v198, s[84:85]
	s_waitcnt lgkmcnt(0)
	s_barrier
	v_mfma_f32_16x16x32_bf16 v[124:127], v[128:131], v[144:147], v[124:127]
	v_mfma_f32_16x16x32_bf16 v[120:123], v[136:139], v[144:147], v[120:123]
	v_mfma_f32_16x16x32_bf16 v[116:119], v[128:131], v[152:155], v[116:119]
	v_mfma_f32_16x16x32_bf16 v[112:115], v[136:139], v[152:155], v[112:115]
	v_mfma_f32_16x16x32_bf16 v[108:111], v[128:131], v[160:163], v[108:111]
	v_mfma_f32_16x16x32_bf16 v[104:107], v[136:139], v[160:163], v[104:107]
	v_mfma_f32_16x16x32_bf16 v[100:103], v[128:131], v[168:171], v[100:103]
	v_mfma_f32_16x16x32_bf16 v[96:99], v[136:139], v[168:171], v[96:99]
	v_mfma_f32_16x16x32_bf16 v[124:127], v[132:135], v[148:151], v[124:127]
	v_mfma_f32_16x16x32_bf16 v[120:123], v[140:143], v[148:151], v[120:123]
	v_mfma_f32_16x16x32_bf16 v[116:119], v[132:135], v[156:159], v[116:119]
	v_mfma_f32_16x16x32_bf16 v[112:115], v[140:143], v[156:159], v[112:115]
	v_mfma_f32_16x16x32_bf16 v[108:111], v[132:135], v[164:167], v[108:111]
	v_mfma_f32_16x16x32_bf16 v[104:107], v[140:143], v[164:167], v[104:107]
	v_mfma_f32_16x16x32_bf16 v[100:103], v[132:135], v[172:175], v[100:103]
	v_mfma_f32_16x16x32_bf16 v[96:99], v[140:143], v[172:175], v[96:99]
	v_mfma_f32_16x16x32_bf16 v[92:95], v[176:179], v[144:147], v[92:95]
	v_mfma_f32_16x16x32_bf16 v[88:91], v[184:187], v[144:147], v[88:91]
	v_mfma_f32_16x16x32_bf16 v[84:87], v[176:179], v[152:155], v[84:87]
	v_mfma_f32_16x16x32_bf16 v[80:83], v[184:187], v[152:155], v[80:83]
	v_mfma_f32_16x16x32_bf16 v[76:79], v[176:179], v[160:163], v[76:79]
	v_mfma_f32_16x16x32_bf16 v[72:75], v[184:187], v[160:163], v[72:75]
	v_mfma_f32_16x16x32_bf16 v[68:71], v[176:179], v[168:171], v[68:71]
	v_mfma_f32_16x16x32_bf16 v[64:67], v[184:187], v[168:171], v[64:67]
	v_mfma_f32_16x16x32_bf16 v[92:95], v[180:183], v[148:151], v[92:95]
	v_mfma_f32_16x16x32_bf16 v[88:91], v[188:191], v[148:151], v[88:91]
	v_mfma_f32_16x16x32_bf16 v[84:87], v[180:183], v[156:159], v[84:87]
	v_mfma_f32_16x16x32_bf16 v[80:83], v[188:191], v[156:159], v[80:83]
	v_mfma_f32_16x16x32_bf16 v[76:79], v[180:183], v[164:167], v[76:79]
	v_mfma_f32_16x16x32_bf16 v[72:75], v[188:191], v[164:167], v[72:75]
	v_mfma_f32_16x16x32_bf16 v[68:71], v[180:183], v[172:175], v[68:71]
	v_mfma_f32_16x16x32_bf16 v[64:67], v[188:191], v[172:175], v[64:67]
	s_add_u32 s84, s46, 0x80
	s_addc_u32 s85, s47, 0
	s_add_u32 s98, s46, 0x40080
	s_addc_u32 s99, s47, 0
	s_barrier
	ds_read_b128 v[144:147], v247 offset:49152
	ds_read_b128 v[148:151], v247 offset:50176
	ds_read_b128 v[152:155], v247 offset:51200
	ds_read_b128 v[156:159], v247 offset:52224
	s_add_i32 m0, s74, 0x18000
	ds_read_b128 v[160:163], v247 offset:53248
	ds_read_b128 v[164:167], v247 offset:54272
	ds_read_b128 v[168:171], v247 offset:55296
	ds_read_b128 v[172:175], v247 offset:56320
	global_load_lds_dwordx4 v192, s[84:85]
	s_add_i32 m0, s74, 0x1a000
	s_nop 0
	global_load_lds_dwordx4 v200, s[84:85]
	s_add_i32 m0, s74, 0x1c000
	s_nop 0
	global_load_lds_dwordx4 v192, s[98:99]
	s_add_i32 m0, s74, 0x1e000
	s_nop 0
	global_load_lds_dwordx4 v200, s[98:99]
	s_waitcnt vmcnt(4)
	s_waitcnt lgkmcnt(0)
	s_barrier
; #define PG8_STAGE(bufoff, gbase, voff) do { _Pragma("unroll") for (int _i = 0; _i < 2; ++_i) \
;         __builtin_amdgcn_global_load_lds((const unsigned*)((const char*)(gbase) + (voff)[_i]), (LAS unsigned*)(lds + (bufoff) + ldsw + _i * 8192), 16, 0, 0); } while (0)
; #define PG8_BAR __builtin_amdgcn_s_barrier()
; template <class Prog>
; __device__ __forceinline__ void gemm_phase(LAS unsigned char* lds, const int K, const Prog& S) {
;     ...
;         for (int t = 0; t < nt; t += 2) {
;             const bool last = (t == nt - 2);
;             const char* a1 = cA + (size_t)(t + 1) * kstep;
;             const char* a2 = last ? nA : cA + (size_t)(t + 2) * kstep; const char* b2 = last ? nB : cB + (size_t)(t + 2) * kstep;
;             const char* a3 = a2 + kstep; const char* b3 = b2 + kstep;
;             PG8_LDB(B0, 0, 0); PG8_SCHED; PG8_LDA(At, 0, 0); PG8_STAGE(PG8_SA(1, 1), a1 + hstep, voffA);
;             PG8_WAIT_L(8); PG8_BAR; PG8_WAIT_L(0); PG8_MMA(0, 0, At, B0); PG8_BAR; PG8_SCHED;
;             PG8_LDB(B1, 0, 1); PG8_STAGE(PG8_SB(0, 0), b2, voffB);
;             PG8_BAR; PG8_WAIT_L(0); PG8_MMA(0, 1, At, B1); PG8_BAR;
;             PG8_LDA(At, 0, 1); PG8_STAGE(PG8_SA(0, 0), a2, voffA);
;             PG8_BAR; PG8_WAIT_L(0); PG8_MMA(1, 0, At, B0); PG8_BAR; PG8_SCHED;
;             PG8_STAGE(PG8_SB(0, 1), b2 + hstep, voffB);
;             PG8_WAIT_V(6); PG8_BAR; PG8_MMA(1, 1, At, B1); PG8_BAR;
;             PG8_LDB(B0, 1, 0); PG8_SCHED; PG8_LDA(At, 1, 0); PG8_STAGE(PG8_SA(0, 1), a2 + hstep, voffA);
;             PG8_WAIT_L(8); PG8_BAR; PG8_WAIT_L(0); PG8_MMA(0, 0, At, B0); PG8_BAR; PG8_SCHED;
;             PG8_LDB(B1, 1, 1); PG8_STAGE(PG8_SB(1, 0), b3, voffB);
;             PG8_BAR; PG8_WAIT_L(0); PG8_MMA(0, 1, At, B1); PG8_BAR;
;             PG8_LDA(At, 1, 1); PG8_STAGE(PG8_SA(1, 0), a3, voffA);
;             PG8_BAR; PG8_WAIT_L(0); PG8_MMA(1, 0, At, B0); PG8_BAR; PG8_SCHED;
;             PG8_STAGE(PG8_SB(1, 1), b3 + hstep, voffB);
;             PG8_WAIT_V(6); PG8_BAR; PG8_MMA(1, 1, At, B1); PG8_BAR;
;     __device__ __forceinline__ void epi(f32x4 (&acc)[2][2][4][2], const pg8::Unit& u, int wr, int wc, int fr, int fq) const {
;         const int row0 = u.pm * 256 + wr * 64 + fr, col0 = u.pn * 256 + wc * 32 + 8 * fq;
;         const int sub = u.sub;
;         u32x4 gn[4][2][2], gd[4][2][2];
;         const int dsub = sub < 2 ? sub + 1 : sub;
	v_mfma_f32_16x16x32_bf16 v[60:63], v[128:131], v[144:147], v[60:63]
	v_mfma_f32_16x16x32_bf16 v[56:59], v[136:139], v[144:147], v[56:59]
	v_mfma_f32_16x16x32_bf16 v[52:55], v[128:131], v[152:155], v[52:55]
	v_mfma_f32_16x16x32_bf16 v[48:51], v[136:139], v[152:155], v[48:51]
	v_mfma_f32_16x16x32_bf16 v[44:47], v[128:131], v[160:163], v[44:47]
	v_mfma_f32_16x16x32_bf16 v[40:43], v[136:139], v[160:163], v[40:43]
	v_mfma_f32_16x16x32_bf16 v[36:39], v[128:131], v[168:171], v[36:39]
	v_mfma_f32_16x16x32_bf16 v[32:35], v[136:139], v[168:171], v[32:35]
	v_mfma_f32_16x16x32_bf16 v[60:63], v[132:135], v[148:151], v[60:63]
	v_mfma_f32_16x16x32_bf16 v[56:59], v[140:143], v[148:151], v[56:59]
	v_mfma_f32_16x16x32_bf16 v[52:55], v[132:135], v[156:159], v[52:55]
	v_mfma_f32_16x16x32_bf16 v[48:51], v[140:143], v[156:159], v[48:51]
	v_mfma_f32_16x16x32_bf16 v[44:47], v[132:135], v[164:167], v[44:47]
	v_mfma_f32_16x16x32_bf16 v[40:43], v[140:143], v[164:167], v[40:43]
	v_mfma_f32_16x16x32_bf16 v[36:39], v[132:135], v[172:175], v[36:39]
	v_mfma_f32_16x16x32_bf16 v[32:35], v[140:143], v[172:175], v[32:35]
	v_mfma_f32_16x16x32_bf16 v[28:31], v[176:179], v[144:147], v[28:31]
	v_mfma_f32_16x16x32_bf16 v[24:27], v[184:187], v[144:147], v[24:27]
	v_mfma_f32_16x16x32_bf16 v[20:23], v[176:179], v[152:155], v[20:23]
	v_mfma_f32_16x16x32_bf16 v[16:19], v[184:187], v[152:155], v[16:19]
	v_mfma_f32_16x16x32_bf16 v[12:15], v[176:179], v[160:163], v[12:15]
	v_mfma_f32_16x16x32_bf16 v[8:11], v[184:187], v[160:163], v[8:11]
	v_mfma_f32_16x16x32_bf16 v[4:7], v[176:179], v[168:171], v[4:7]
	v_mfma_f32_16x16x32_bf16 v[0:3], v[184:187], v[168:171], v[0:3]
	v_mfma_f32_16x16x32_bf16 v[28:31], v[180:183], v[148:151], v[28:31]
	v_mfma_f32_16x16x32_bf16 v[24:27], v[188:191], v[148:151], v[24:27]
	v_mfma_f32_16x16x32_bf16 v[20:23], v[180:183], v[156:159], v[20:23]
	v_mfma_f32_16x16x32_bf16 v[16:19], v[188:191], v[156:159], v[16:19]
	v_mfma_f32_16x16x32_bf16 v[12:15], v[180:183], v[164:167], v[12:15]
	v_mfma_f32_16x16x32_bf16 v[8:11], v[188:191], v[164:167], v[8:11]
	v_mfma_f32_16x16x32_bf16 v[4:7], v[180:183], v[172:175], v[4:7]
	v_mfma_f32_16x16x32_bf16 v[0:3], v[188:191], v[172:175], v[0:3]
	s_add_i32 s55, s55, 2
	s_add_u32 s44, s44, 0x100
	s_addc_u32 s45, s45, 0
	s_add_u32 s41, s41, 0x100
	s_addc_u32 s43, s43, 0
	s_add_u32 s46, s44, 0xfffc0080
	s_addc_u32 s47, s45, -1
	s_cmp_eq_u32 s55, 12
	s_cselect_b32 s53, s7, s47
	s_cselect_b32 s52, s6, s46
	s_cselect_b32 s47, s9, s43
	s_cselect_b32 s46, s8, s41
	s_add_u32 s84, s44, 0xfffc0000
	s_addc_u32 s85, s45, -1
	s_cmp_gt_u32 s55, 13
	s_barrier
	s_cbranch_scc0 .LBB0_400
	s_cmp_lt_i32 s14, 2
	v_lshl_add_u32 v208, s15, 8, v244
	v_lshl_or_b32 v206, s54, 8, v246
	s_cselect_b64 s[8:9], -1, 0
	s_cmp_gt_i32 s14, 1
	v_mov_b64_e32 v[128:129], s[26:27]
	s_cselect_b64 s[92:93], -1, 0
	s_cmp_lg_u64 s[8:9], 0
	v_ashrrev_i32_e32 v207, 31, v206
	v_mad_i64_i32 v[128:129], s[6:7], v208, s58, v[128:129]
	s_addc_u32 s15, s14, 0
	s_lshl_b32 s46, s14, 11
	v_lshl_add_u64 v[128:129], v[206:207], 1, v[128:129]
	s_ashr_i32 s47, s46, 31
	v_lshl_add_u64 v[128:129], v[128:129], 0, s[34:35]
	v_lshl_add_u64 v[130:131], s[46:47], 1, v[128:129]
	global_load_dwordx4 v[188:191], v[130:131], off
	s_lshl_b32 s52, s15, 11
	s_ashr_i32 s53, s52, 31
	v_mov_b32_e32 v148, 0
	s_and_b64 vcc, exec, s[92:93]
	v_lshl_add_u64 v[128:129], s[52:53], 1, v[128:129]
	v_mov_b32_e32 v180, 0
	v_mov_b32_e32 v181, 0
	v_mov_b32_e32 v182, 0
	v_mov_b32_e32 v183, 0
	s_cbranch_vccnz .LBB0_403
	global_load_dwordx4 v[180:183], v[128:129], off

; #define PG8_STAGE(bufoff, gbase, voff) do { _Pragma("unroll") for (int _i = 0; _i < 2; ++_i) \
;         __builtin_amdgcn_global_load_lds((const unsigned*)((const char*)(gbase) + (voff)[_i]), (LAS unsigned*)(lds + (bufoff) + ldsw + _i * 8192), 16, 0, 0); } while (0)
; #define PG8_LDA(dst, b, h) do { _Pragma("unroll") for (int m = 0; m < 4; ++m) _Pragma("unroll") for (int k = 0; k < 2; ++k) dst[m][k] = *(const LAS bf16x8*)(lds + PG8_SA(b, h) + aoff + m * 2048 + k * 1024); } while (0)
; #define PG8_WAIT_V(n) asm volatile("s_waitcnt vmcnt(" #n ")" ::: "memory")
; template <class Prog>
; __device__ __forceinline__ void gemm_phase(LAS unsigned char* lds, const int K, const Prog& S) {
;     ...
;         const char* nA = has_next ? nxt.a : cA; const char* nB = has_next ? nxt.b : cB;
;         for (int t = 0; t < nt; t += 2) {
;             const bool last = (t == nt - 2);
;             const char* a1 = cA + (size_t)(t + 1) * kstep;
;             const char* a2 = last ? nA : cA + (size_t)(t + 2) * kstep; const char* b2 = last ? nB : cB + (size_t)(t + 2) * kstep;
;             const char* a3 = a2 + kstep; const char* b3 = b2 + kstep;
;             PG8_LDB(B0, 0, 0); PG8_SCHED; PG8_LDA(At, 0, 0); PG8_STAGE(PG8_SA(1, 1), a1 + hstep, voffA);
;             PG8_WAIT_L(8); PG8_BAR; PG8_WAIT_L(0); PG8_MMA(0, 0, At, B0); PG8_BAR; PG8_SCHED;
;             PG8_LDB(B1, 0, 1); PG8_STAGE(PG8_SB(0, 0), b2, voffB);
;             PG8_BAR; PG8_WAIT_L(0); PG8_MMA(0, 1, At, B1); PG8_BAR;
;             PG8_LDA(At, 0, 1); PG8_STAGE(PG8_SA(0, 0), a2, voffA);
;             PG8_BAR; PG8_WAIT_L(0); PG8_MMA(1, 0, At, B0); PG8_BAR; PG8_SCHED;
;             PG8_STAGE(PG8_SB(0, 1), b2 + hstep, voffB);
;             PG8_WAIT_V(6); PG8_BAR; PG8_MMA(1, 1, At, B1); PG8_BAR;
;             PG8_LDB(B0, 1, 0); PG8_SCHED; PG8_LDA(At, 1, 0); PG8_STAGE(PG8_SA(0, 1), a2 + hstep, voffA);
;             PG8_WAIT_L(8); PG8_BAR; PG8_WAIT_L(0); PG8_MMA(0, 0, At, B0); PG8_BAR; PG8_SCHED;
;             PG8_LDB(B1, 1, 1); PG8_STAGE(PG8_SB(1, 0), b3, voffB);
;             PG8_BAR; PG8_WAIT_L(0); PG8_MMA(0, 1, At, B1); PG8_BAR;
;             PG8_LDA(At, 1, 1); PG8_STAGE(PG8_SA(1, 0), a3, voffA);
;             PG8_BAR; PG8_WAIT_L(0); PG8_MMA(1, 0, At, B0); PG8_BAR; PG8_SCHED;
;             PG8_STAGE(PG8_SB(1, 1), b3 + hstep, voffB);
;             PG8_WAIT_V(6); PG8_BAR; PG8_MMA(1, 1, At, B1); PG8_BAR;
.LBB0_570:
	s_add_u32 s46, s46, 0x80080
	s_addc_u32 s47, s47, 0
	s_add_u32 s41, s52, 0x100
	s_addc_u32 s43, s53, 0
	s_mov_b32 s54, -2
	s_waitcnt lgkmcnt(0)
	s_waitcnt vmcnt(16)
	v_add_u32_e32 v202, 0x10000, v215
	s_add_u32 s52, s46, 0xfff80080
	s_addc_u32 s53, s47, -1
	s_cmp_eq_u32 s54, 28
	s_cselect_b32 s93, s7, s53
	s_cselect_b32 s92, s6, s52
	s_cselect_b32 s53, s45, s43
	s_cselect_b32 s52, s44, s41
	s_add_u32 vcc_lo, s46, 0xfff80000
	s_addc_u32 vcc_hi, s47, -1
	ds_read_b128 v[128:131], v202
	ds_read_b128 v[132:135], v202 offset:1024
	ds_read_b128 v[136:139], v202 offset:2048
	ds_read_b128 v[140:143], v202 offset:3072
	s_add_i32 m0, s75, 0x8000
	ds_read_b128 v[176:179], v202 offset:16384
	ds_read_b128 v[180:183], v202 offset:17408
	ds_read_b128 v[184:187], v202 offset:18432
	ds_read_b128 v[198:201], v202 offset:19456
	global_load_lds_dwordx4 v190, vcc
	s_add_i32 m0, s75, 0xa000
	ds_read_b128 v[144:147], v217
	ds_read_b128 v[148:151], v217 offset:1024
	ds_read_b128 v[152:155], v217 offset:2048
	ds_read_b128 v[156:159], v217 offset:3072
	global_load_lds_dwordx4 v196, vcc
	s_add_i32 m0, s75, 0xc000
	ds_read_b128 v[160:163], v217 offset:4096
	ds_read_b128 v[164:167], v217 offset:5120
	ds_read_b128 v[168:171], v217 offset:6144
	ds_read_b128 v[172:175], v217 offset:7168
	global_load_lds_dwordx4 v190, s[46:47]
	s_add_i32 m0, s75, 0xe000
	s_nop 0
	global_load_lds_dwordx4 v196, s[46:47]
	s_waitcnt lgkmcnt(0)
	s_barrier
	v_mfma_f32_16x16x32_bf16 v[124:127], v[128:131], v[144:147], 0
	v_mfma_f32_16x16x32_bf16 v[120:123], v[136:139], v[144:147], 0
	v_mfma_f32_16x16x32_bf16 v[108:111], v[128:131], v[152:155], 0
	v_mfma_f32_16x16x32_bf16 v[104:107], v[136:139], v[152:155], 0
	v_mfma_f32_16x16x32_bf16 v[92:95], v[128:131], v[160:163], 0
	v_mfma_f32_16x16x32_bf16 v[88:91], v[136:139], v[160:163], 0
	v_mfma_f32_16x16x32_bf16 v[76:79], v[128:131], v[168:171], 0
	v_mfma_f32_16x16x32_bf16 v[72:75], v[136:139], v[168:171], 0
	v_mfma_f32_16x16x32_bf16 v[124:127], v[132:135], v[148:151], v[124:127]
	v_mfma_f32_16x16x32_bf16 v[120:123], v[140:143], v[148:151], v[120:123]
	v_mfma_f32_16x16x32_bf16 v[108:111], v[132:135], v[156:159], v[108:111]
	v_mfma_f32_16x16x32_bf16 v[104:107], v[140:143], v[156:159], v[104:107]
	v_mfma_f32_16x16x32_bf16 v[92:95], v[132:135], v[164:167], v[92:95]
	v_mfma_f32_16x16x32_bf16 v[88:91], v[140:143], v[164:167], v[88:91]
	v_mfma_f32_16x16x32_bf16 v[76:79], v[132:135], v[172:175], v[76:79]
	v_mfma_f32_16x16x32_bf16 v[72:75], v[140:143], v[172:175], v[72:75]
	v_mfma_f32_16x16x32_bf16 v[116:119], v[176:179], v[144:147], 0
	v_mfma_f32_16x16x32_bf16 v[112:115], v[184:187], v[144:147], 0
	v_mfma_f32_16x16x32_bf16 v[100:103], v[176:179], v[152:155], 0
	v_mfma_f32_16x16x32_bf16 v[96:99], v[184:187], v[152:155], 0
	v_mfma_f32_16x16x32_bf16 v[84:87], v[176:179], v[160:163], 0
	v_mfma_f32_16x16x32_bf16 v[80:83], v[184:187], v[160:163], 0
	v_mfma_f32_16x16x32_bf16 v[68:71], v[176:179], v[168:171], 0
	v_mfma_f32_16x16x32_bf16 v[64:67], v[184:187], v[168:171], 0
	v_mfma_f32_16x16x32_bf16 v[116:119], v[180:183], v[148:151], v[116:119]
	v_mfma_f32_16x16x32_bf16 v[112:115], v[198:201], v[148:151], v[112:115]
	v_mfma_f32_16x16x32_bf16 v[100:103], v[180:183], v[156:159], v[100:103]
	v_mfma_f32_16x16x32_bf16 v[96:99], v[198:201], v[156:159], v[96:99]
	v_mfma_f32_16x16x32_bf16 v[84:87], v[180:183], v[164:167], v[84:87]
	v_mfma_f32_16x16x32_bf16 v[80:83], v[198:201], v[164:167], v[80:83]
	v_mfma_f32_16x16x32_bf16 v[68:71], v[180:183], v[172:175], v[68:71]
	v_mfma_f32_16x16x32_bf16 v[64:67], v[198:201], v[172:175], v[64:67]
	s_add_u32 vcc_lo, s52, 0x80000
	s_addc_u32 vcc_hi, s53, 0
	s_barrier
	ds_read_b128 v[144:147], v217 offset:16384
	ds_read_b128 v[148:151], v217 offset:17408
	ds_read_b128 v[152:155], v217 offset:18432
	ds_read_b128 v[156:159], v217 offset:19456
	s_add_i32 m0, s75, 0x10000
	ds_read_b128 v[160:163], v217 offset:20480
	ds_read_b128 v[164:167], v217 offset:21504
	ds_read_b128 v[168:171], v217 offset:22528
	ds_read_b128 v[172:175], v217 offset:23552
	global_load_lds_dwordx4 v192, s[52:53]
	s_add_i32 m0, s75, 0x12000
	s_nop 0
	global_load_lds_dwordx4 v188, s[52:53]
	s_add_i32 m0, s75, 0x14000
	s_nop 0
	global_load_lds_dwordx4 v192, vcc
	s_add_i32 m0, s75, 0x16000
	s_nop 0
	global_load_lds_dwordx4 v188, vcc
	s_waitcnt vmcnt(4)
	s_waitcnt lgkmcnt(0)
	s_barrier
	v_mfma_f32_16x16x32_bf16 v[60:63], v[128:131], v[144:147], 0
	v_mfma_f32_16x16x32_bf16 v[56:59], v[136:139], v[144:147], 0
	v_mfma_f32_16x16x32_bf16 v[44:47], v[128:131], v[152:155], 0
	v_mfma_f32_16x16x32_bf16 v[40:43], v[136:139], v[152:155], 0
	v_mfma_f32_16x16x32_bf16 v[28:31], v[128:131], v[160:163], 0
	v_mfma_f32_16x16x32_bf16 v[24:27], v[136:139], v[160:163], 0
	v_mfma_f32_16x16x32_bf16 v[12:15], v[128:131], v[168:171], 0
	v_mfma_f32_16x16x32_bf16 v[8:11], v[136:139], v[168:171], 0
	v_mfma_f32_16x16x32_bf16 v[60:63], v[132:135], v[148:151], v[60:63]
	v_mfma_f32_16x16x32_bf16 v[56:59], v[140:143], v[148:151], v[56:59]
	v_mfma_f32_16x16x32_bf16 v[44:47], v[132:135], v[156:159], v[44:47]
	v_mfma_f32_16x16x32_bf16 v[40:43], v[140:143], v[156:159], v[40:43]
	v_mfma_f32_16x16x32_bf16 v[28:31], v[132:135], v[164:167], v[28:31]
	v_mfma_f32_16x16x32_bf16 v[24:27], v[140:143], v[164:167], v[24:27]
	v_mfma_f32_16x16x32_bf16 v[12:15], v[132:135], v[172:175], v[12:15]
	v_mfma_f32_16x16x32_bf16 v[8:11], v[140:143], v[172:175], v[8:11]
	v_mfma_f32_16x16x32_bf16 v[52:55], v[176:179], v[144:147], 0
	v_mfma_f32_16x16x32_bf16 v[48:51], v[184:187], v[144:147], 0
	v_mfma_f32_16x16x32_bf16 v[36:39], v[176:179], v[152:155], 0
	v_mfma_f32_16x16x32_bf16 v[32:35], v[184:187], v[152:155], 0
	v_mfma_f32_16x16x32_bf16 v[20:23], v[176:179], v[160:163], 0
	v_mfma_f32_16x16x32_bf16 v[16:19], v[184:187], v[160:163], 0
	v_mfma_f32_16x16x32_bf16 v[4:7], v[176:179], v[168:171], 0
	v_mfma_f32_16x16x32_bf16 v[0:3], v[184:187], v[168:171], 0
	v_mfma_f32_16x16x32_bf16 v[52:55], v[180:183], v[148:151], v[52:55]
	v_mfma_f32_16x16x32_bf16 v[48:51], v[198:201], v[148:151], v[48:51]
	v_mfma_f32_16x16x32_bf16 v[36:39], v[180:183], v[156:159], v[36:39]
	v_mfma_f32_16x16x32_bf16 v[32:35], v[198:201], v[156:159], v[32:35]
	v_mfma_f32_16x16x32_bf16 v[20:23], v[180:183], v[164:167], v[20:23]
	v_mfma_f32_16x16x32_bf16 v[16:19], v[198:201], v[164:167], v[16:19]
	v_mfma_f32_16x16x32_bf16 v[4:7], v[180:183], v[172:175], v[4:7]
	v_mfma_f32_16x16x32_bf16 v[0:3], v[198:201], v[172:175], v[0:3]
	s_add_u32 vcc_lo, s92, 0x80000
	s_addc_u32 vcc_hi, s93, 0
	s_barrier
; #define PG8_STAGE(bufoff, gbase, voff) do { _Pragma("unroll") for (int _i = 0; _i < 2; ++_i) \
;         __builtin_amdgcn_global_load_lds((const unsigned*)((const char*)(gbase) + (voff)[_i]), (LAS unsigned*)(lds + (bufoff) + ldsw + _i * 8192), 16, 0, 0); } while (0)
; #define PG8_LDA(dst, b, h) do { _Pragma("unroll") for (int m = 0; m < 4; ++m) _Pragma("unroll") for (int k = 0; k < 2; ++k) dst[m][k] = *(const LAS bf16x8*)(lds + PG8_SA(b, h) + aoff + m * 2048 + k * 1024); } while (0)
; #define PG8_WAIT_V(n) asm volatile("s_waitcnt vmcnt(" #n ")" ::: "memory")
; #define PG8_WAIT_L(n) asm volatile("s_waitcnt lgkmcnt(" #n ")" ::: "memory")
; template <class Prog>
; __device__ __forceinline__ void gemm_phase(LAS unsigned char* lds, const int K, const Prog& S) {
;     ...
;         for (int t = 0; t < nt; t += 2) {
;             const bool last = (t == nt - 2);
;             const char* a1 = cA + (size_t)(t + 1) * kstep;
;             const char* a2 = last ? nA : cA + (size_t)(t + 2) * kstep; const char* b2 = last ? nB : cB + (size_t)(t + 2) * kstep;
;             const char* a3 = a2 + kstep; const char* b3 = b2 + kstep;
;             PG8_LDB(B0, 0, 0); PG8_SCHED; PG8_LDA(At, 0, 0); PG8_STAGE(PG8_SA(1, 1), a1 + hstep, voffA);
;             PG8_WAIT_L(8); PG8_BAR; PG8_WAIT_L(0); PG8_MMA(0, 0, At, B0); PG8_BAR; PG8_SCHED;
;             PG8_LDB(B1, 0, 1); PG8_STAGE(PG8_SB(0, 0), b2, voffB);
;             PG8_BAR; PG8_WAIT_L(0); PG8_MMA(0, 1, At, B1); PG8_BAR;
;             PG8_LDA(At, 0, 1); PG8_STAGE(PG8_SA(0, 0), a2, voffA);
;             PG8_BAR; PG8_WAIT_L(0); PG8_MMA(1, 0, At, B0); PG8_BAR; PG8_SCHED;
;             PG8_STAGE(PG8_SB(0, 1), b2 + hstep, voffB);
;             PG8_WAIT_V(6); PG8_BAR; PG8_MMA(1, 1, At, B1); PG8_BAR;
;             PG8_LDB(B0, 1, 0); PG8_SCHED; PG8_LDA(At, 1, 0); PG8_STAGE(PG8_SA(0, 1), a2 + hstep, voffA);
;             PG8_WAIT_L(8); PG8_BAR; PG8_WAIT_L(0); PG8_MMA(0, 0, At, B0); PG8_BAR; PG8_SCHED;
;             PG8_LDB(B1, 1, 1); PG8_STAGE(PG8_SB(1, 0), b3, voffB);
;             PG8_BAR; PG8_WAIT_L(0); PG8_MMA(0, 1, At, B1); PG8_BAR;
;             PG8_LDA(At, 1, 1); PG8_STAGE(PG8_SA(1, 0), a3, voffA);
;             PG8_BAR; PG8_WAIT_L(0); PG8_MMA(1, 0, At, B0); PG8_BAR; PG8_SCHED;
;             PG8_STAGE(PG8_SB(1, 1), b3 + hstep, voffB);
;             PG8_WAIT_V(6); PG8_BAR; PG8_MMA(1, 1, At, B1); PG8_BAR;
	ds_read_b128 v[128:131], v202 offset:32768
	ds_read_b128 v[132:135], v202 offset:33792
	ds_read_b128 v[136:139], v202 offset:34816
	ds_read_b128 v[140:143], v202 offset:35840
	s_mov_b32 m0, s75
	ds_read_b128 v[176:179], v202 offset:49152
	ds_read_b128 v[180:183], v202 offset:50176
	ds_read_b128 v[184:187], v202 offset:51200
	ds_read_b128 v[198:201], v202 offset:52224
	global_load_lds_dwordx4 v192, s[92:93]
	s_add_i32 m0, s75, 0x2000
	ds_read_b128 v[144:147], v217 offset:32768
	ds_read_b128 v[148:151], v217 offset:33792
	ds_read_b128 v[152:155], v217 offset:34816
	ds_read_b128 v[156:159], v217 offset:35840
	global_load_lds_dwordx4 v188, s[92:93]
	s_add_i32 m0, s75, 0x4000
	ds_read_b128 v[160:163], v217 offset:36864
	ds_read_b128 v[164:167], v217 offset:37888
	ds_read_b128 v[168:171], v217 offset:38912
	ds_read_b128 v[172:175], v217 offset:39936
	global_load_lds_dwordx4 v192, vcc
	s_add_i32 m0, s75, 0x6000
	s_nop 0
	global_load_lds_dwordx4 v188, vcc
	s_waitcnt lgkmcnt(0)
	s_barrier
	v_mfma_f32_16x16x32_bf16 v[124:127], v[128:131], v[144:147], v[124:127]
	v_mfma_f32_16x16x32_bf16 v[120:123], v[136:139], v[144:147], v[120:123]
	v_mfma_f32_16x16x32_bf16 v[108:111], v[128:131], v[152:155], v[108:111]
	v_mfma_f32_16x16x32_bf16 v[104:107], v[136:139], v[152:155], v[104:107]
	v_mfma_f32_16x16x32_bf16 v[92:95], v[128:131], v[160:163], v[92:95]
	v_mfma_f32_16x16x32_bf16 v[88:91], v[136:139], v[160:163], v[88:91]
	v_mfma_f32_16x16x32_bf16 v[76:79], v[128:131], v[168:171], v[76:79]
	v_mfma_f32_16x16x32_bf16 v[72:75], v[136:139], v[168:171], v[72:75]
	v_mfma_f32_16x16x32_bf16 v[124:127], v[132:135], v[148:151], v[124:127]
	v_mfma_f32_16x16x32_bf16 v[120:123], v[140:143], v[148:151], v[120:123]
	v_mfma_f32_16x16x32_bf16 v[108:111], v[132:135], v[156:159], v[108:111]
	v_mfma_f32_16x16x32_bf16 v[104:107], v[140:143], v[156:159], v[104:107]
	v_mfma_f32_16x16x32_bf16 v[92:95], v[132:135], v[164:167], v[92:95]
	v_mfma_f32_16x16x32_bf16 v[88:91], v[140:143], v[164:167], v[88:91]
	v_mfma_f32_16x16x32_bf16 v[76:79], v[132:135], v[172:175], v[76:79]
	v_mfma_f32_16x16x32_bf16 v[72:75], v[140:143], v[172:175], v[72:75]
	v_mfma_f32_16x16x32_bf16 v[116:119], v[176:179], v[144:147], v[116:119]
	v_mfma_f32_16x16x32_bf16 v[112:115], v[184:187], v[144:147], v[112:115]
	v_mfma_f32_16x16x32_bf16 v[100:103], v[176:179], v[152:155], v[100:103]
	v_mfma_f32_16x16x32_bf16 v[96:99], v[184:187], v[152:155], v[96:99]
	v_mfma_f32_16x16x32_bf16 v[84:87], v[176:179], v[160:163], v[84:87]
	v_mfma_f32_16x16x32_bf16 v[80:83], v[184:187], v[160:163], v[80:83]
	v_mfma_f32_16x16x32_bf16 v[68:71], v[176:179], v[168:171], v[68:71]
	v_mfma_f32_16x16x32_bf16 v[64:67], v[184:187], v[168:171], v[64:67]
	v_mfma_f32_16x16x32_bf16 v[116:119], v[180:183], v[148:151], v[116:119]
	v_mfma_f32_16x16x32_bf16 v[112:115], v[198:201], v[148:151], v[112:115]
	v_mfma_f32_16x16x32_bf16 v[100:103], v[180:183], v[156:159], v[100:103]
	v_mfma_f32_16x16x32_bf16 v[96:99], v[198:201], v[156:159], v[96:99]
	v_mfma_f32_16x16x32_bf16 v[84:87], v[180:183], v[164:167], v[84:87]
	v_mfma_f32_16x16x32_bf16 v[80:83], v[198:201], v[164:167], v[80:83]
	v_mfma_f32_16x16x32_bf16 v[68:71], v[180:183], v[172:175], v[68:71]
	v_mfma_f32_16x16x32_bf16 v[64:67], v[198:201], v[172:175], v[64:67]
	s_add_u32 vcc_lo, s52, 0x80
	s_addc_u32 vcc_hi, s53, 0
	s_add_u32 s98, s52, 0x80080
	s_addc_u32 s99, s53, 0
	s_barrier
	ds_read_b128 v[144:147], v217 offset:49152
	ds_read_b128 v[148:151], v217 offset:50176
	ds_read_b128 v[152:155], v217 offset:51200
	ds_read_b128 v[156:159], v217 offset:52224
	s_add_i32 m0, s75, 0x18000
	ds_read_b128 v[160:163], v217 offset:53248
	ds_read_b128 v[164:167], v217 offset:54272
	ds_read_b128 v[168:171], v217 offset:55296
	ds_read_b128 v[172:175], v217 offset:56320
	global_load_lds_dwordx4 v192, vcc
	s_add_i32 m0, s75, 0x1a000
	s_nop 0
	global_load_lds_dwordx4 v188, vcc
	s_add_i32 m0, s75, 0x1c000
	s_nop 0
	global_load_lds_dwordx4 v192, s[98:99]
	s_add_i32 m0, s75, 0x1e000
	s_nop 0
	global_load_lds_dwordx4 v188, s[98:99]
	s_waitcnt vmcnt(4)
	s_waitcnt lgkmcnt(0)
	s_barrier
	v_mfma_f32_16x16x32_bf16 v[60:63], v[128:131], v[144:147], v[60:63]
	v_mfma_f32_16x16x32_bf16 v[56:59], v[136:139], v[144:147], v[56:59]
	v_mfma_f32_16x16x32_bf16 v[44:47], v[128:131], v[152:155], v[44:47]
	v_mfma_f32_16x16x32_bf16 v[40:43], v[136:139], v[152:155], v[40:43]
	v_mfma_f32_16x16x32_bf16 v[28:31], v[128:131], v[160:163], v[28:31]
	v_mfma_f32_16x16x32_bf16 v[24:27], v[136:139], v[160:163], v[24:27]
	v_mfma_f32_16x16x32_bf16 v[12:15], v[128:131], v[168:171], v[12:15]
	v_mfma_f32_16x16x32_bf16 v[8:11], v[136:139], v[168:171], v[8:11]
	v_mfma_f32_16x16x32_bf16 v[60:63], v[132:135], v[148:151], v[60:63]
	v_mfma_f32_16x16x32_bf16 v[56:59], v[140:143], v[148:151], v[56:59]
	v_mfma_f32_16x16x32_bf16 v[44:47], v[132:135], v[156:159], v[44:47]
	v_mfma_f32_16x16x32_bf16 v[40:43], v[140:143], v[156:159], v[40:43]
	v_mfma_f32_16x16x32_bf16 v[28:31], v[132:135], v[164:167], v[28:31]
	v_mfma_f32_16x16x32_bf16 v[24:27], v[140:143], v[164:167], v[24:27]
	v_mfma_f32_16x16x32_bf16 v[12:15], v[132:135], v[172:175], v[12:15]
	v_mfma_f32_16x16x32_bf16 v[8:11], v[140:143], v[172:175], v[8:11]
	v_mfma_f32_16x16x32_bf16 v[52:55], v[176:179], v[144:147], v[52:55]
	v_mfma_f32_16x16x32_bf16 v[48:51], v[184:187], v[144:147], v[48:51]
	v_mfma_f32_16x16x32_bf16 v[36:39], v[176:179], v[152:155], v[36:39]
	v_mfma_f32_16x16x32_bf16 v[32:35], v[184:187], v[152:155], v[32:35]
	v_mfma_f32_16x16x32_bf16 v[20:23], v[176:179], v[160:163], v[20:23]
	v_mfma_f32_16x16x32_bf16 v[16:19], v[184:187], v[160:163], v[16:19]
	v_mfma_f32_16x16x32_bf16 v[4:7], v[176:179], v[168:171], v[4:7]
	v_mfma_f32_16x16x32_bf16 v[0:3], v[184:187], v[168:171], v[0:3]
	v_mfma_f32_16x16x32_bf16 v[52:55], v[180:183], v[148:151], v[52:55]
	v_mfma_f32_16x16x32_bf16 v[48:51], v[198:201], v[148:151], v[48:51]
	v_mfma_f32_16x16x32_bf16 v[36:39], v[180:183], v[156:159], v[36:39]
	v_mfma_f32_16x16x32_bf16 v[32:35], v[198:201], v[156:159], v[32:35]
	v_mfma_f32_16x16x32_bf16 v[20:23], v[180:183], v[164:167], v[20:23]
	v_mfma_f32_16x16x32_bf16 v[16:19], v[198:201], v[164:167], v[16:19]
	v_mfma_f32_16x16x32_bf16 v[4:7], v[180:183], v[172:175], v[4:7]
	v_mfma_f32_16x16x32_bf16 v[0:3], v[198:201], v[172:175], v[0:3]
	s_add_i32 s54, s54, 2
	s_add_u32 s46, s46, 0x100
	s_addc_u32 s47, s47, 0
	s_add_u32 s41, s41, 0x100
	s_addc_u32 s43, s43, 0
	s_add_u32 s52, s46, 0xfff80080
	s_addc_u32 s53, s47, -1
	s_cmp_eq_u32 s54, 28
	s_cselect_b32 s93, s7, s53
	s_cselect_b32 s92, s6, s52
	s_cselect_b32 s53, s45, s43
	s_cselect_b32 s52, s44, s41
	s_add_u32 vcc_lo, s46, 0xfff80000
	s_addc_u32 vcc_hi, s47, -1
	s_cmp_gt_u32 s54, 29
	s_barrier
	.p2align 6
; #define PG8_STAGE(bufoff, gbase, voff) do { _Pragma("unroll") for (int _i = 0; _i < 2; ++_i) \
;         __builtin_amdgcn_global_load_lds((const unsigned*)((const char*)(gbase) + (voff)[_i]), (LAS unsigned*)(lds + (bufoff) + ldsw + _i * 8192), 16, 0, 0); } while (0)
; #define PG8_LDA(dst, b, h) do { _Pragma("unroll") for (int m = 0; m < 4; ++m) _Pragma("unroll") for (int k = 0; k < 2; ++k) dst[m][k] = *(const LAS bf16x8*)(lds + PG8_SA(b, h) + aoff + m * 2048 + k * 1024); } while (0)
; #define PG8_WAIT_V(n) asm volatile("s_waitcnt vmcnt(" #n ")" ::: "memory")
; #define PG8_WAIT_L(n) asm volatile("s_waitcnt lgkmcnt(" #n ")" ::: "memory")
; template <class Prog>
; __device__ __forceinline__ void gemm_phase(LAS unsigned char* lds, const int K, const Prog& S) {
;     ...
;         for (int t = 0; t < nt; t += 2) {
;             const bool last = (t == nt - 2);
;             const char* a1 = cA + (size_t)(t + 1) * kstep;
;             const char* a2 = last ? nA : cA + (size_t)(t + 2) * kstep; const char* b2 = last ? nB : cB + (size_t)(t + 2) * kstep;
;             const char* a3 = a2 + kstep; const char* b3 = b2 + kstep;
;             PG8_LDB(B0, 0, 0); PG8_SCHED; PG8_LDA(At, 0, 0); PG8_STAGE(PG8_SA(1, 1), a1 + hstep, voffA);
;             PG8_WAIT_L(8); PG8_BAR; PG8_WAIT_L(0); PG8_MMA(0, 0, At, B0); PG8_BAR; PG8_SCHED;
;             PG8_LDB(B1, 0, 1); PG8_STAGE(PG8_SB(0, 0), b2, voffB);
;             PG8_BAR; PG8_WAIT_L(0); PG8_MMA(0, 1, At, B1); PG8_BAR;
;             PG8_LDA(At, 0, 1); PG8_STAGE(PG8_SA(0, 0), a2, voffA);
;             PG8_BAR; PG8_WAIT_L(0); PG8_MMA(1, 0, At, B0); PG8_BAR; PG8_SCHED;
;             PG8_STAGE(PG8_SB(0, 1), b2 + hstep, voffB);
;             PG8_WAIT_V(6); PG8_BAR; PG8_MMA(1, 1, At, B1); PG8_BAR;
;             PG8_LDB(B0, 1, 0); PG8_SCHED; PG8_LDA(At, 1, 0); PG8_STAGE(PG8_SA(0, 1), a2 + hstep, voffA);
;             PG8_WAIT_L(8); PG8_BAR; PG8_WAIT_L(0); PG8_MMA(0, 0, At, B0); PG8_BAR; PG8_SCHED;
;             PG8_LDB(B1, 1, 1); PG8_STAGE(PG8_SB(1, 0), b3, voffB);
;             PG8_BAR; PG8_WAIT_L(0); PG8_MMA(0, 1, At, B1); PG8_BAR;
;             PG8_LDA(At, 1, 1); PG8_STAGE(PG8_SA(1, 0), a3, voffA);
;             PG8_BAR; PG8_WAIT_L(0); PG8_MMA(1, 0, At, B0); PG8_BAR; PG8_SCHED;
;             PG8_STAGE(PG8_SB(1, 1), b3 + hstep, voffB);
;             PG8_WAIT_V(6); PG8_BAR; PG8_MMA(1, 1, At, B1); PG8_BAR;
.LBB0_571:
	ds_read_b128 v[128:131], v202
	ds_read_b128 v[132:135], v202 offset:1024
	ds_read_b128 v[136:139], v202 offset:2048
	ds_read_b128 v[140:143], v202 offset:3072
	s_add_i32 m0, s75, 0x8000
	ds_read_b128 v[176:179], v202 offset:16384
	ds_read_b128 v[180:183], v202 offset:17408
	ds_read_b128 v[184:187], v202 offset:18432
	ds_read_b128 v[198:201], v202 offset:19456
	global_load_lds_dwordx4 v190, vcc
	s_add_i32 m0, s75, 0xa000
	ds_read_b128 v[144:147], v217
	ds_read_b128 v[148:151], v217 offset:1024
	ds_read_b128 v[152:155], v217 offset:2048
	ds_read_b128 v[156:159], v217 offset:3072
	global_load_lds_dwordx4 v196, vcc
	s_add_i32 m0, s75, 0xc000
	ds_read_b128 v[160:163], v217 offset:4096
	ds_read_b128 v[164:167], v217 offset:5120
	ds_read_b128 v[168:171], v217 offset:6144
	ds_read_b128 v[172:175], v217 offset:7168
	global_load_lds_dwordx4 v190, s[46:47]
	s_add_i32 m0, s75, 0xe000
	s_nop 0
	global_load_lds_dwordx4 v196, s[46:47]
	s_waitcnt lgkmcnt(0)
	s_barrier
	v_mfma_f32_16x16x32_bf16 v[124:127], v[128:131], v[144:147], v[124:127]
	v_mfma_f32_16x16x32_bf16 v[120:123], v[136:139], v[144:147], v[120:123]
	v_mfma_f32_16x16x32_bf16 v[108:111], v[128:131], v[152:155], v[108:111]
	v_mfma_f32_16x16x32_bf16 v[104:107], v[136:139], v[152:155], v[104:107]
	v_mfma_f32_16x16x32_bf16 v[92:95], v[128:131], v[160:163], v[92:95]
	v_mfma_f32_16x16x32_bf16 v[88:91], v[136:139], v[160:163], v[88:91]
	v_mfma_f32_16x16x32_bf16 v[76:79], v[128:131], v[168:171], v[76:79]
	v_mfma_f32_16x16x32_bf16 v[72:75], v[136:139], v[168:171], v[72:75]
	v_mfma_f32_16x16x32_bf16 v[124:127], v[132:135], v[148:151], v[124:127]
	v_mfma_f32_16x16x32_bf16 v[120:123], v[140:143], v[148:151], v[120:123]
	v_mfma_f32_16x16x32_bf16 v[108:111], v[132:135], v[156:159], v[108:111]
	v_mfma_f32_16x16x32_bf16 v[104:107], v[140:143], v[156:159], v[104:107]
	v_mfma_f32_16x16x32_bf16 v[92:95], v[132:135], v[164:167], v[92:95]
	v_mfma_f32_16x16x32_bf16 v[88:91], v[140:143], v[164:167], v[88:91]
	v_mfma_f32_16x16x32_bf16 v[76:79], v[132:135], v[172:175], v[76:79]
	v_mfma_f32_16x16x32_bf16 v[72:75], v[140:143], v[172:175], v[72:75]
	v_mfma_f32_16x16x32_bf16 v[116:119], v[176:179], v[144:147], v[116:119]
	v_mfma_f32_16x16x32_bf16 v[112:115], v[184:187], v[144:147], v[112:115]
	v_mfma_f32_16x16x32_bf16 v[100:103], v[176:179], v[152:155], v[100:103]
	v_mfma_f32_16x16x32_bf16 v[96:99], v[184:187], v[152:155], v[96:99]
	v_mfma_f32_16x16x32_bf16 v[84:87], v[176:179], v[160:163], v[84:87]
	v_mfma_f32_16x16x32_bf16 v[80:83], v[184:187], v[160:163], v[80:83]
	v_mfma_f32_16x16x32_bf16 v[68:71], v[176:179], v[168:171], v[68:71]
	v_mfma_f32_16x16x32_bf16 v[64:67], v[184:187], v[168:171], v[64:67]
	v_mfma_f32_16x16x32_bf16 v[116:119], v[180:183], v[148:151], v[116:119]
	v_mfma_f32_16x16x32_bf16 v[112:115], v[198:201], v[148:151], v[112:115]
	v_mfma_f32_16x16x32_bf16 v[100:103], v[180:183], v[156:159], v[100:103]
	v_mfma_f32_16x16x32_bf16 v[96:99], v[198:201], v[156:159], v[96:99]
	v_mfma_f32_16x16x32_bf16 v[84:87], v[180:183], v[164:167], v[84:87]
	v_mfma_f32_16x16x32_bf16 v[80:83], v[198:201], v[164:167], v[80:83]
	v_mfma_f32_16x16x32_bf16 v[68:71], v[180:183], v[172:175], v[68:71]
	v_mfma_f32_16x16x32_bf16 v[64:67], v[198:201], v[172:175], v[64:67]
	s_add_u32 vcc_lo, s52, 0x80000
	s_addc_u32 vcc_hi, s53, 0
	s_barrier
	ds_read_b128 v[144:147], v217 offset:16384
	ds_read_b128 v[148:151], v217 offset:17408
	ds_read_b128 v[152:155], v217 offset:18432
	ds_read_b128 v[156:159], v217 offset:19456
	s_add_i32 m0, s75, 0x10000
	ds_read_b128 v[160:163], v217 offset:20480
	ds_read_b128 v[164:167], v217 offset:21504
	ds_read_b128 v[168:171], v217 offset:22528
	ds_read_b128 v[172:175], v217 offset:23552
	global_load_lds_dwordx4 v192, s[52:53]
	s_add_i32 m0, s75, 0x12000
	s_nop 0
	global_load_lds_dwordx4 v188, s[52:53]
	s_add_i32 m0, s75, 0x14000
	s_nop 0
	global_load_lds_dwordx4 v192, vcc
	s_add_i32 m0, s75, 0x16000
	s_nop 0
	global_load_lds_dwordx4 v188, vcc
	s_waitcnt vmcnt(4)
	s_waitcnt lgkmcnt(0)
	s_barrier
	v_mfma_f32_16x16x32_bf16 v[60:63], v[128:131], v[144:147], v[60:63]
	v_mfma_f32_16x16x32_bf16 v[56:59], v[136:139], v[144:147], v[56:59]
	v_mfma_f32_16x16x32_bf16 v[44:47], v[128:131], v[152:155], v[44:47]
	v_mfma_f32_16x16x32_bf16 v[40:43], v[136:139], v[152:155], v[40:43]
	v_mfma_f32_16x16x32_bf16 v[28:31], v[128:131], v[160:163], v[28:31]
	v_mfma_f32_16x16x32_bf16 v[24:27], v[136:139], v[160:163], v[24:27]
	v_mfma_f32_16x16x32_bf16 v[12:15], v[128:131], v[168:171], v[12:15]
	v_mfma_f32_16x16x32_bf16 v[8:11], v[136:139], v[168:171], v[8:11]
	v_mfma_f32_16x16x32_bf16 v[60:63], v[132:135], v[148:151], v[60:63]
	v_mfma_f32_16x16x32_bf16 v[56:59], v[140:143], v[148:151], v[56:59]
	v_mfma_f32_16x16x32_bf16 v[44:47], v[132:135], v[156:159], v[44:47]
	v_mfma_f32_16x16x32_bf16 v[40:43], v[140:143], v[156:159], v[40:43]
	v_mfma_f32_16x16x32_bf16 v[28:31], v[132:135], v[164:167], v[28:31]
	v_mfma_f32_16x16x32_bf16 v[24:27], v[140:143], v[164:167], v[24:27]
	v_mfma_f32_16x16x32_bf16 v[12:15], v[132:135], v[172:175], v[12:15]
	v_mfma_f32_16x16x32_bf16 v[8:11], v[140:143], v[172:175], v[8:11]
	v_mfma_f32_16x16x32_bf16 v[52:55], v[176:179], v[144:147], v[52:55]
	v_mfma_f32_16x16x32_bf16 v[48:51], v[184:187], v[144:147], v[48:51]
	v_mfma_f32_16x16x32_bf16 v[36:39], v[176:179], v[152:155], v[36:39]
	v_mfma_f32_16x16x32_bf16 v[32:35], v[184:187], v[152:155], v[32:35]
	v_mfma_f32_16x16x32_bf16 v[20:23], v[176:179], v[160:163], v[20:23]
	v_mfma_f32_16x16x32_bf16 v[16:19], v[184:187], v[160:163], v[16:19]
	v_mfma_f32_16x16x32_bf16 v[4:7], v[176:179], v[168:171], v[4:7]
	v_mfma_f32_16x16x32_bf16 v[0:3], v[184:187], v[168:171], v[0:3]
	v_mfma_f32_16x16x32_bf16 v[52:55], v[180:183], v[148:151], v[52:55]
	v_mfma_f32_16x16x32_bf16 v[48:51], v[198:201], v[148:151], v[48:51]
	v_mfma_f32_16x16x32_bf16 v[36:39], v[180:183], v[156:159], v[36:39]
	v_mfma_f32_16x16x32_bf16 v[32:35], v[198:201], v[156:159], v[32:35]
	v_mfma_f32_16x16x32_bf16 v[20:23], v[180:183], v[164:167], v[20:23]
	v_mfma_f32_16x16x32_bf16 v[16:19], v[198:201], v[164:167], v[16:19]
	v_mfma_f32_16x16x32_bf16 v[4:7], v[180:183], v[172:175], v[4:7]
	v_mfma_f32_16x16x32_bf16 v[0:3], v[198:201], v[172:175], v[0:3]
	s_add_u32 vcc_lo, s92, 0x80000
	s_addc_u32 vcc_hi, s93, 0
	s_barrier
; #define PG8_STAGE(bufoff, gbase, voff) do { _Pragma("unroll") for (int _i = 0; _i < 2; ++_i) \
;         __builtin_amdgcn_global_load_lds((const unsigned*)((const char*)(gbase) + (voff)[_i]), (LAS unsigned*)(lds + (bufoff) + ldsw + _i * 8192), 16, 0, 0); } while (0)
; #define PG8_LDA(dst, b, h) do { _Pragma("unroll") for (int m = 0; m < 4; ++m) _Pragma("unroll") for (int k = 0; k < 2; ++k) dst[m][k] = *(const LAS bf16x8*)(lds + PG8_SA(b, h) + aoff + m * 2048 + k * 1024); } while (0)
; #define PG8_WAIT_V(n) asm volatile("s_waitcnt vmcnt(" #n ")" ::: "memory")
; #define PG8_WAIT_L(n) asm volatile("s_waitcnt lgkmcnt(" #n ")" ::: "memory")
; template <class Prog>
; __device__ __forceinline__ void gemm_phase(LAS unsigned char* lds, const int K, const Prog& S) {
;     ...
;         for (int t = 0; t < nt; t += 2) {
;             const bool last = (t == nt - 2);
;             const char* a1 = cA + (size_t)(t + 1) * kstep;
;             const char* a2 = last ? nA : cA + (size_t)(t + 2) * kstep; const char* b2 = last ? nB : cB + (size_t)(t + 2) * kstep;
;             const char* a3 = a2 + kstep; const char* b3 = b2 + kstep;
;             PG8_LDB(B0, 0, 0); PG8_SCHED; PG8_LDA(At, 0, 0); PG8_STAGE(PG8_SA(1, 1), a1 + hstep, voffA);
;             PG8_WAIT_L(8); PG8_BAR; PG8_WAIT_L(0); PG8_MMA(0, 0, At, B0); PG8_BAR; PG8_SCHED;
;             PG8_LDB(B1, 0, 1); PG8_STAGE(PG8_SB(0, 0), b2, voffB);
;             PG8_BAR; PG8_WAIT_L(0); PG8_MMA(0, 1, At, B1); PG8_BAR;
;             PG8_LDA(At, 0, 1); PG8_STAGE(PG8_SA(0, 0), a2, voffA);
;             PG8_BAR; PG8_WAIT_L(0); PG8_MMA(1, 0, At, B0); PG8_BAR; PG8_SCHED;
;             PG8_STAGE(PG8_SB(0, 1), b2 + hstep, voffB);
;             PG8_WAIT_V(6); PG8_BAR; PG8_MMA(1, 1, At, B1); PG8_BAR;
;             PG8_LDB(B0, 1, 0); PG8_SCHED; PG8_LDA(At, 1, 0); PG8_STAGE(PG8_SA(0, 1), a2 + hstep, voffA);
;             PG8_WAIT_L(8); PG8_BAR; PG8_WAIT_L(0); PG8_MMA(0, 0, At, B0); PG8_BAR; PG8_SCHED;
;             PG8_LDB(B1, 1, 1); PG8_STAGE(PG8_SB(1, 0), b3, voffB);
;             PG8_BAR; PG8_WAIT_L(0); PG8_MMA(0, 1, At, B1); PG8_BAR;
;             PG8_LDA(At, 1, 1); PG8_STAGE(PG8_SA(1, 0), a3, voffA);
;             PG8_BAR; PG8_WAIT_L(0); PG8_MMA(1, 0, At, B0); PG8_BAR; PG8_SCHED;
;             PG8_STAGE(PG8_SB(1, 1), b3 + hstep, voffB);
;             PG8_WAIT_V(6); PG8_BAR; PG8_MMA(1, 1, At, B1); PG8_BAR;
	ds_read_b128 v[128:131], v202 offset:32768
	ds_read_b128 v[132:135], v202 offset:33792
	ds_read_b128 v[136:139], v202 offset:34816
	ds_read_b128 v[140:143], v202 offset:35840
	s_mov_b32 m0, s75
	ds_read_b128 v[176:179], v202 offset:49152
	ds_read_b128 v[180:183], v202 offset:50176
	ds_read_b128 v[184:187], v202 offset:51200
	ds_read_b128 v[198:201], v202 offset:52224
	global_load_lds_dwordx4 v192, s[92:93]
	s_add_i32 m0, s75, 0x2000
	ds_read_b128 v[144:147], v217 offset:32768
	ds_read_b128 v[148:151], v217 offset:33792
	ds_read_b128 v[152:155], v217 offset:34816
	ds_read_b128 v[156:159], v217 offset:35840
	global_load_lds_dwordx4 v188, s[92:93]
	s_add_i32 m0, s75, 0x4000
	ds_read_b128 v[160:163], v217 offset:36864
	ds_read_b128 v[164:167], v217 offset:37888
	ds_read_b128 v[168:171], v217 offset:38912
	ds_read_b128 v[172:175], v217 offset:39936
	global_load_lds_dwordx4 v192, vcc
	s_add_i32 m0, s75, 0x6000
	s_nop 0
	global_load_lds_dwordx4 v188, vcc
	s_waitcnt lgkmcnt(0)
	s_barrier
	v_mfma_f32_16x16x32_bf16 v[124:127], v[128:131], v[144:147], v[124:127]
	v_mfma_f32_16x16x32_bf16 v[120:123], v[136:139], v[144:147], v[120:123]
	v_mfma_f32_16x16x32_bf16 v[108:111], v[128:131], v[152:155], v[108:111]
	v_mfma_f32_16x16x32_bf16 v[104:107], v[136:139], v[152:155], v[104:107]
	v_mfma_f32_16x16x32_bf16 v[92:95], v[128:131], v[160:163], v[92:95]
	v_mfma_f32_16x16x32_bf16 v[88:91], v[136:139], v[160:163], v[88:91]
	v_mfma_f32_16x16x32_bf16 v[76:79], v[128:131], v[168:171], v[76:79]
	v_mfma_f32_16x16x32_bf16 v[72:75], v[136:139], v[168:171], v[72:75]
	v_mfma_f32_16x16x32_bf16 v[124:127], v[132:135], v[148:151], v[124:127]
	v_mfma_f32_16x16x32_bf16 v[120:123], v[140:143], v[148:151], v[120:123]
	v_mfma_f32_16x16x32_bf16 v[108:111], v[132:135], v[156:159], v[108:111]
	v_mfma_f32_16x16x32_bf16 v[104:107], v[140:143], v[156:159], v[104:107]
	v_mfma_f32_16x16x32_bf16 v[92:95], v[132:135], v[164:167], v[92:95]
	v_mfma_f32_16x16x32_bf16 v[88:91], v[140:143], v[164:167], v[88:91]
	v_mfma_f32_16x16x32_bf16 v[76:79], v[132:135], v[172:175], v[76:79]
	v_mfma_f32_16x16x32_bf16 v[72:75], v[140:143], v[172:175], v[72:75]
	v_mfma_f32_16x16x32_bf16 v[116:119], v[176:179], v[144:147], v[116:119]
	v_mfma_f32_16x16x32_bf16 v[112:115], v[184:187], v[144:147], v[112:115]
	v_mfma_f32_16x16x32_bf16 v[100:103], v[176:179], v[152:155], v[100:103]
	v_mfma_f32_16x16x32_bf16 v[96:99], v[184:187], v[152:155], v[96:99]
	v_mfma_f32_16x16x32_bf16 v[84:87], v[176:179], v[160:163], v[84:87]
	v_mfma_f32_16x16x32_bf16 v[80:83], v[184:187], v[160:163], v[80:83]
	v_mfma_f32_16x16x32_bf16 v[68:71], v[176:179], v[168:171], v[68:71]
	v_mfma_f32_16x16x32_bf16 v[64:67], v[184:187], v[168:171], v[64:67]
	v_mfma_f32_16x16x32_bf16 v[116:119], v[180:183], v[148:151], v[116:119]
	v_mfma_f32_16x16x32_bf16 v[112:115], v[198:201], v[148:151], v[112:115]
	v_mfma_f32_16x16x32_bf16 v[100:103], v[180:183], v[156:159], v[100:103]
	v_mfma_f32_16x16x32_bf16 v[96:99], v[198:201], v[156:159], v[96:99]
	v_mfma_f32_16x16x32_bf16 v[84:87], v[180:183], v[164:167], v[84:87]
	v_mfma_f32_16x16x32_bf16 v[80:83], v[198:201], v[164:167], v[80:83]
	v_mfma_f32_16x16x32_bf16 v[68:71], v[180:183], v[172:175], v[68:71]
	v_mfma_f32_16x16x32_bf16 v[64:67], v[198:201], v[172:175], v[64:67]
	s_add_u32 vcc_lo, s52, 0x80
	s_addc_u32 vcc_hi, s53, 0
	s_add_u32 s98, s52, 0x80080
	s_addc_u32 s99, s53, 0
	s_barrier
	ds_read_b128 v[144:147], v217 offset:49152
	ds_read_b128 v[148:151], v217 offset:50176
	ds_read_b128 v[152:155], v217 offset:51200
	ds_read_b128 v[156:159], v217 offset:52224
	s_add_i32 m0, s75, 0x18000
	ds_read_b128 v[160:163], v217 offset:53248
	ds_read_b128 v[164:167], v217 offset:54272
	ds_read_b128 v[168:171], v217 offset:55296
	ds_read_b128 v[172:175], v217 offset:56320
	global_load_lds_dwordx4 v192, vcc
	s_add_i32 m0, s75, 0x1a000
	s_nop 0
	global_load_lds_dwordx4 v188, vcc
	s_add_i32 m0, s75, 0x1c000
	s_nop 0
	global_load_lds_dwordx4 v192, s[98:99]
	s_add_i32 m0, s75, 0x1e000
	s_nop 0
	global_load_lds_dwordx4 v188, s[98:99]
	s_waitcnt vmcnt(4)
	s_waitcnt lgkmcnt(0)
	s_barrier
; template <class Prog>
; __device__ __forceinline__ void gemm_phase(LAS unsigned char* lds, const int K, const Prog& S) {
;     ...
;         for (int t = 0; t < nt; t += 2) {
;             const bool last = (t == nt - 2);
;             const char* a1 = cA + (size_t)(t + 1) * kstep;
;             const char* a2 = last ? nA : cA + (size_t)(t + 2) * kstep; const char* b2 = last ? nB : cB + (size_t)(t + 2) * kstep;
;             const char* a3 = a2 + kstep; const char* b3 = b2 + kstep;
;             PG8_LDB(B0, 0, 0); PG8_SCHED; PG8_LDA(At, 0, 0); PG8_STAGE(PG8_SA(1, 1), a1 + hstep, voffA);
;             PG8_WAIT_L(8); PG8_BAR; PG8_WAIT_L(0); PG8_MMA(0, 0, At, B0); PG8_BAR; PG8_SCHED;
;             PG8_LDB(B1, 0, 1); PG8_STAGE(PG8_SB(0, 0), b2, voffB);
;             PG8_BAR; PG8_WAIT_L(0); PG8_MMA(0, 1, At, B1); PG8_BAR;
;             PG8_LDA(At, 0, 1); PG8_STAGE(PG8_SA(0, 0), a2, voffA);
;             PG8_BAR; PG8_WAIT_L(0); PG8_MMA(1, 0, At, B0); PG8_BAR; PG8_SCHED;
;             PG8_STAGE(PG8_SB(0, 1), b2 + hstep, voffB);
;             PG8_WAIT_V(6); PG8_BAR; PG8_MMA(1, 1, At, B1); PG8_BAR;
;             PG8_LDB(B0, 1, 0); PG8_SCHED; PG8_LDA(At, 1, 0); PG8_STAGE(PG8_SA(0, 1), a2 + hstep, voffA);
;             PG8_WAIT_L(8); PG8_BAR; PG8_WAIT_L(0); PG8_MMA(0, 0, At, B0); PG8_BAR; PG8_SCHED;
;             PG8_LDB(B1, 1, 1); PG8_STAGE(PG8_SB(1, 0), b3, voffB);
;             PG8_BAR; PG8_WAIT_L(0); PG8_MMA(0, 1, At, B1); PG8_BAR;
;             PG8_LDA(At, 1, 1); PG8_STAGE(PG8_SA(1, 0), a3, voffA);
;             PG8_BAR; PG8_WAIT_L(0); PG8_MMA(1, 0, At, B0); PG8_BAR; PG8_SCHED;
;             PG8_STAGE(PG8_SB(1, 1), b3 + hstep, voffB);
;             PG8_WAIT_V(6); PG8_BAR; PG8_MMA(1, 1, At, B1); PG8_BAR;
;     __device__ __forceinline__ void epi(f32x4 (&acc)[2][2][4][2], const pg8::Unit& u, int wr, int wc, int fr, int fq) const {
;         const int row0 = u.pm * 256 + wr * 64 + fr, col0 = u.pn * 256 + wc * 32 + 4 * fq;
; #pragma unroll
;         for (int ai = 0; ai < 2; ++ai) {
;             f32x4 xo[4][2][2];
; #pragma unroll
;             for (int m = 0; m < 4; ++m)
; #pragma unroll
;                 for (int bj = 0; bj < 2; ++bj)
; #pragma unroll
;                     for (int n = 0; n < 2; ++n) xo[m][bj][n] = *(const f32x4*)(xin + (size_t)(row0 + ai * 128 + m * 16) * DM + col0 + bj * 128 + n * 16);
; #pragma unroll
;             for (int m = 0; m < 4; ++m) {
	v_mfma_f32_16x16x32_bf16 v[60:63], v[128:131], v[144:147], v[60:63]
	v_mfma_f32_16x16x32_bf16 v[56:59], v[136:139], v[144:147], v[56:59]
	v_mfma_f32_16x16x32_bf16 v[44:47], v[128:131], v[152:155], v[44:47]
	v_mfma_f32_16x16x32_bf16 v[40:43], v[136:139], v[152:155], v[40:43]
	v_mfma_f32_16x16x32_bf16 v[28:31], v[128:131], v[160:163], v[28:31]
	v_mfma_f32_16x16x32_bf16 v[24:27], v[136:139], v[160:163], v[24:27]
	v_mfma_f32_16x16x32_bf16 v[12:15], v[128:131], v[168:171], v[12:15]
	v_mfma_f32_16x16x32_bf16 v[8:11], v[136:139], v[168:171], v[8:11]
	v_mfma_f32_16x16x32_bf16 v[60:63], v[132:135], v[148:151], v[60:63]
	v_mfma_f32_16x16x32_bf16 v[56:59], v[140:143], v[148:151], v[56:59]
	v_mfma_f32_16x16x32_bf16 v[44:47], v[132:135], v[156:159], v[44:47]
	v_mfma_f32_16x16x32_bf16 v[40:43], v[140:143], v[156:159], v[40:43]
	v_mfma_f32_16x16x32_bf16 v[28:31], v[132:135], v[164:167], v[28:31]
	v_mfma_f32_16x16x32_bf16 v[24:27], v[140:143], v[164:167], v[24:27]
	v_mfma_f32_16x16x32_bf16 v[12:15], v[132:135], v[172:175], v[12:15]
	v_mfma_f32_16x16x32_bf16 v[8:11], v[140:143], v[172:175], v[8:11]
	v_mfma_f32_16x16x32_bf16 v[52:55], v[176:179], v[144:147], v[52:55]
	v_mfma_f32_16x16x32_bf16 v[48:51], v[184:187], v[144:147], v[48:51]
	v_mfma_f32_16x16x32_bf16 v[36:39], v[176:179], v[152:155], v[36:39]
	v_mfma_f32_16x16x32_bf16 v[32:35], v[184:187], v[152:155], v[32:35]
	v_mfma_f32_16x16x32_bf16 v[20:23], v[176:179], v[160:163], v[20:23]
	v_mfma_f32_16x16x32_bf16 v[16:19], v[184:187], v[160:163], v[16:19]
	v_mfma_f32_16x16x32_bf16 v[4:7], v[176:179], v[168:171], v[4:7]
	v_mfma_f32_16x16x32_bf16 v[0:3], v[184:187], v[168:171], v[0:3]
	v_mfma_f32_16x16x32_bf16 v[52:55], v[180:183], v[148:151], v[52:55]
	v_mfma_f32_16x16x32_bf16 v[48:51], v[198:201], v[148:151], v[48:51]
	v_mfma_f32_16x16x32_bf16 v[36:39], v[180:183], v[156:159], v[36:39]
	v_mfma_f32_16x16x32_bf16 v[32:35], v[198:201], v[156:159], v[32:35]
	v_mfma_f32_16x16x32_bf16 v[20:23], v[180:183], v[164:167], v[20:23]
	v_mfma_f32_16x16x32_bf16 v[16:19], v[198:201], v[164:167], v[16:19]
	v_mfma_f32_16x16x32_bf16 v[4:7], v[180:183], v[172:175], v[4:7]
	v_mfma_f32_16x16x32_bf16 v[0:3], v[198:201], v[172:175], v[0:3]
	s_add_i32 s54, s54, 2
	s_add_u32 s46, s46, 0x100
	s_addc_u32 s47, s47, 0
	s_add_u32 s41, s41, 0x100
	s_addc_u32 s43, s43, 0
	s_add_u32 s52, s46, 0xfff80080
	s_addc_u32 s53, s47, -1
	s_cmp_eq_u32 s54, 28
	s_cselect_b32 s93, s7, s53
	s_cselect_b32 s92, s6, s52
	s_cselect_b32 s53, s45, s43
	s_cselect_b32 s52, s44, s41
	s_add_u32 vcc_lo, s46, 0xfff80000
	s_addc_u32 vcc_hi, s47, -1
	s_cmp_gt_u32 s54, 29
	s_barrier
	s_cbranch_scc0 .LBB0_571
	v_lshl_add_u32 v202, s80, 8, v214
	v_lshl_or_b32 v198, s73, 8, v216
	v_ashrrev_i32_e32 v199, 31, v198
	v_ashrrev_i32_e32 v203, 31, v202
	v_lshl_add_u64 v[200:201], v[198:199], 2, s[8:9]
	v_lshlrev_b64 v[128:129], 13, v[202:203]
	v_or_b32_e32 v208, 16, v202
	v_lshl_add_u64 v[128:129], v[200:201], 0, v[128:129]
	v_ashrrev_i32_e32 v209, 31, v208
	global_load_dwordx4 v[210:213], v[128:129], off
	global_load_dwordx4 v[184:187], v[128:129], off offset:64
	global_load_dwordx4 v[180:183], v[128:129], off offset:512
	global_load_dwordx4 v[176:179], v[128:129], off offset:576
	v_lshlrev_b64 v[128:129], 13, v[208:209]
	v_or_b32_e32 v206, 32, v202
	v_lshl_add_u64 v[128:129], v[200:201], 0, v[128:129]
	v_ashrrev_i32_e32 v207, 31, v206
	global_load_dwordx4 v[172:175], v[128:129], off
	global_load_dwordx4 v[168:171], v[128:129], off offset:64
	global_load_dwordx4 v[164:167], v[128:129], off offset:512
	global_load_dwordx4 v[160:163], v[128:129], off offset:576
	v_lshlrev_b64 v[128:129], 13, v[206:207]
	v_or_b32_e32 v204, 48, v202
	v_lshl_add_u64 v[128:129], v[200:201], 0, v[128:129]
	v_ashrrev_i32_e32 v205, 31, v204
	global_load_dwordx4 v[156:159], v[128:129], off
	global_load_dwordx4 v[152:155], v[128:129], off offset:64
	global_load_dwordx4 v[148:151], v[128:129], off offset:512
	global_load_dwordx4 v[144:147], v[128:129], off offset:576
	v_lshlrev_b64 v[128:129], 13, v[204:205]
	v_lshl_add_u64 v[128:129], v[200:201], 0, v[128:129]
	global_load_dwordx4 v[140:143], v[128:129], off
	global_load_dwordx4 v[136:139], v[128:129], off offset:64
	global_load_dwordx4 v[132:135], v[128:129], off offset:512
	s_nop 0
	global_load_dwordx4 v[128:131], v[128:129], off offset:576
	v_lshlrev_b64 v[218:219], 11, v[202:203]
	v_lshl_add_u64 v[218:219], v[218:219], 0, v[198:199]
	s_andn2_b64 vcc, exec, s[12:13]
	s_waitcnt vmcnt(0)
	v_pk_add_f32 v[126:127], v[126:127], v[212:213]
	v_cndmask_b32_e64 v212, 0, 1, s[12:13]
	v_pk_add_f32 v[124:125], v[124:125], v[210:211]
	v_lshl_add_u64 v[210:211], v[218:219], 2, s[48:49]
	v_cmp_ne_u32_e64 s[6:7], 1, v212
	v_lshl_add_u64 v[212:213], v[218:219], 1, s[20:21]
	global_store_dwordx4 v[210:211], v[124:127], off
	s_cbranch_vccnz .LBB0_574
	v_cvt_pk_bf16_f32 v218, v124, v125
	v_cvt_pk_bf16_f32 v219, v126, v127
	global_store_dwordx2 v[212:213], v[218:219], off

; __global__ void __launch_bounds__(NTHR, 2) mk_fwd(Args a) {
;     extern __shared__ __attribute__((aligned(16))) unsigned char lds_raw[];
	.amdhsa_kernel _Z6mk_fwd4Args
		.amdhsa_group_segment_fixed_size 0
		.amdhsa_private_segment_fixed_size 0
		.amdhsa_kernarg_size 392
		.amdhsa_user_sgpr_count 2
		.amdhsa_user_sgpr_dispatch_ptr 0
		.amdhsa_user_sgpr_queue_ptr 0
		.amdhsa_user_sgpr_kernarg_segment_ptr 1
		.amdhsa_user_sgpr_dispatch_id 0
		.amdhsa_user_sgpr_kernarg_preload_length 0
		.amdhsa_user_sgpr_kernarg_preload_offset 0
		.amdhsa_user_sgpr_private_segment_size 0
		.amdhsa_uses_dynamic_stack 0
		.amdhsa_enable_private_segment 0
		.amdhsa_system_sgpr_workgroup_id_x 1
		.amdhsa_system_sgpr_workgroup_id_y 0
		.amdhsa_system_sgpr_workgroup_id_z 0
		.amdhsa_system_sgpr_workgroup_info 0
		.amdhsa_system_vgpr_workitem_id 2
		.amdhsa_next_free_vgpr 256
		.amdhsa_next_free_sgpr 102
		.amdhsa_accum_offset 256
		.amdhsa_reserve_vcc 1
		.amdhsa_float_round_mode_32 0
		.amdhsa_float_round_mode_16_64 0
		.amdhsa_float_denorm_mode_32 3
		.amdhsa_float_denorm_mode_16_64 3
		.amdhsa_dx10_clamp 1
		.amdhsa_ieee_mode 1
		.amdhsa_fp16_overflow 0
		.amdhsa_tg_split 0
		.amdhsa_exception_fp_ieee_invalid_op 0
		.amdhsa_exception_fp_denorm_src 0
		.amdhsa_exception_fp_ieee_div_zero 0
		.amdhsa_exception_fp_ieee_overflow 0
		.amdhsa_exception_fp_ieee_underflow 0
		.amdhsa_exception_fp_ieee_inexact 0
		.amdhsa_exception_int_div_zero 0
	.end_amdhsa_kernel

; __global__ void __launch_bounds__(NTHR, 2) mk_fwd(Args a) {
;     extern __shared__ __attribute__((aligned(16))) unsigned char lds_raw[];
amdhsa.kernels:
  - .agpr_count:     0
    .args:
      - .offset:         0
        .size:           136
        .value_kind:     by_value
      - .offset:         136
        .size:           4
        .value_kind:     hidden_block_count_x
      - .offset:         140
        .size:           4
        .value_kind:     hidden_block_count_y
      - .offset:         144
        .size:           4
        .value_kind:     hidden_block_count_z
      - .offset:         148
        .size:           2
        .value_kind:     hidden_group_size_x
      - .offset:         150
        .size:           2
        .value_kind:     hidden_group_size_y
      - .offset:         152
        .size:           2
        .value_kind:     hidden_group_size_z
      - .offset:         154
        .size:           2
        .value_kind:     hidden_remainder_x
      - .offset:         156
        .size:           2
        .value_kind:     hidden_remainder_y
      - .offset:         158
        .size:           2
        .value_kind:     hidden_remainder_z
      - .offset:         176
        .size:           8
        .value_kind:     hidden_global_offset_x
      - .offset:         184
        .size:           8
        .value_kind:     hidden_global_offset_y
      - .offset:         192
        .size:           8
        .value_kind:     hidden_global_offset_z
      - .offset:         200
        .size:           2
        .value_kind:     hidden_grid_dims
      - .offset:         224
        .size:           8
        .value_kind:     hidden_multigrid_sync_arg
      - .offset:         256
        .size:           4
        .value_kind:     hidden_dynamic_lds_size
    .group_segment_fixed_size: 0
    .kernarg_segment_align: 8
    .kernarg_segment_size: 392
    .language:       OpenCL C
    .language_version:
      - 2
      - 0
    .max_flat_workgroup_size: 512
    .name:           _Z6mk_fwd4Args
    .private_segment_fixed_size: 0
    .sgpr_count:     108
    .sgpr_spill_count: 92
    .symbol:         _Z6mk_fwd4Args.kd
    .uniform_work_group_size: 1
    .uses_dynamic_stack: false
    .vgpr_count:     256
    .vgpr_spill_count: 0
    .wavefront_size: 64
